# EpiMerge epilogues: gate/prev loads hoisted and batched (1 and 3 waits per tile instead of 16 and 32)
# speedup vs baseline: 1.0422x; 1.0093x over previous
.LBB0_1027:
	s_mov_b32 s26, s76
	v_mov_b32_e32 v141, v147
	s_mov_b32 s27, s34
	v_mov_b32_e32 v140, v146
	v_mov_b32_e32 v142, s90
	ds_read_b64 v[142:143], v142
	s_lshl_b32 s16, s16, 8
	s_lshl_b32 s26, s26, 5
	s_add_i32 s26, s26, s16
	s_lshl_b32 s37, s37, 8
	s_lshl_b32 s46, s27, 6
	v_lshl_add_u32 v140, v140, 3, s26
	s_waitcnt lgkmcnt(0)
	v_readfirstlane_b32 s26, v142
	v_readfirstlane_b32 s16, v143
	s_add_u32 s28, s26, 0x8bf0000
	s_addc_u32 s29, s16, 0
	s_add_u32 s26, s26, 0x4bf0000
	s_addc_u32 s27, s16, 0
	s_add_i32 s46, s46, s37
	v_add_u32_e32 v142, s46, v141
	v_mov_b64_e32 v[144:145], s[28:29]
	v_ashrrev_i32_e32 v141, 31, v140
	v_mad_i64_i32 v[150:151], s[28:29], v142, s95, v[144:145]
	v_lshlrev_b64 v[140:141], 1, v[140:141]
	v_lshl_add_u64 v[150:151], v[150:151], 0, v[140:141]
	s_mov_b64 s[46:47], 0x1e80
	s_movk_i32 s16, 0x1000
	v_ashrrev_i32_e32 v143, 31, v142
	v_lshl_add_u64 v[156:157], v[150:151], 0, s[46:47]
	v_add_co_u32_e32 v150, vcc, s16, v150
	v_lshlrev_b64 v[152:153], 11, v[142:143]
	s_nop 0
	v_addc_co_u32_e32 v151, vcc, 0, v151, vcc
	v_lshl_add_u64 v[154:155], s[26:27], 0, v[152:153]
	flat_load_dwordx4 v[150:153], v[150:151] offset:3712
	v_lshl_add_u64 v[246:247], v[144:145], 0, v[140:141]
	v_lshl_add_u64 v[246:247], v[246:247], 0, s[46:47]
	v_mad_i64_i32 v[164:165], s[100:101], v142, s95, v[246:247]
	global_load_dwordx4 v[164:167], v[164:165], off offset:256
	v_add_u32_e32 v170, 16, v142
	v_mad_i64_i32 v[168:169], s[100:101], v170, s95, v[246:247]
	global_load_dwordx4 v[168:171], v[168:169], off
	v_add_u32_e32 v174, 16, v142
	v_mad_i64_i32 v[172:173], s[100:101], v174, s95, v[246:247]
	global_load_dwordx4 v[172:175], v[172:173], off offset:256
	v_add_u32_e32 v178, 32, v142
	v_mad_i64_i32 v[176:177], s[100:101], v178, s95, v[246:247]
	global_load_dwordx4 v[176:179], v[176:177], off
	v_add_u32_e32 v184, 32, v142
	v_mad_i64_i32 v[182:183], s[100:101], v184, s95, v[246:247]
	global_load_dwordx4 v[182:185], v[182:183], off offset:256
	v_add_u32_e32 v188, 48, v142
	v_mad_i64_i32 v[186:187], s[100:101], v188, s95, v[246:247]
	global_load_dwordx4 v[186:189], v[186:187], off
	v_add_u32_e32 v192, 48, v142
	v_mad_i64_i32 v[190:191], s[100:101], v192, s95, v[246:247]
	global_load_dwordx4 v[190:193], v[190:191], off offset:256
	v_add_u32_e32 v196, 128, v142
	v_mad_i64_i32 v[194:195], s[100:101], v196, s95, v[246:247]
	global_load_dwordx4 v[194:197], v[194:195], off
	v_add_u32_e32 v220, 128, v142
	v_mad_i64_i32 v[218:219], s[100:101], v220, s95, v[246:247]
	global_load_dwordx4 v[218:221], v[218:219], off offset:256
	v_add_u32_e32 v224, 144, v142
	v_mad_i64_i32 v[222:223], s[100:101], v224, s95, v[246:247]
	global_load_dwordx4 v[222:225], v[222:223], off
	v_add_u32_e32 v232, 144, v142
	v_mad_i64_i32 v[230:231], s[100:101], v232, s95, v[246:247]
	global_load_dwordx4 v[230:233], v[230:231], off offset:256
	v_add_u32_e32 v236, 160, v142
	v_mad_i64_i32 v[234:235], s[100:101], v236, s95, v[246:247]
	global_load_dwordx4 v[234:237], v[234:235], off
	v_add_u32_e32 v240, 160, v142
	v_mad_i64_i32 v[238:239], s[100:101], v240, s95, v[246:247]
	global_load_dwordx4 v[238:241], v[238:239], off offset:256
	v_add_u32_e32 v244, 176, v142
	v_mad_i64_i32 v[242:243], s[100:101], v244, s95, v[246:247]
	global_load_dwordx4 v[242:245], v[242:243], off
	v_add_u32_e32 v250, 176, v142
	v_mad_i64_i32 v[248:249], s[100:101], v250, s95, v[246:247]
	global_load_dwordx4 v[248:251], v[248:249], off offset:256
	v_lshl_add_u64 v[154:155], v[154:155], 0, v[140:141]
	s_waitcnt vmcnt(0) lgkmcnt(0)
	v_lshlrev_b32_e32 v143, 16, v150
	v_mul_f32_e32 v143, 0xbfb8aa3b, v143
	v_exp_f32_e32 v143, v143
	v_and_b32_e32 v158, 0xffff0000, v150
	v_lshlrev_b32_e32 v159, 16, v151
	v_and_b32_e32 v160, 0xffff0000, v151
	v_add_f32_e32 v143, 1.0, v143
	v_rcp_f32_e32 v150, v143
	v_mul_f32_e32 v143, 0xbfb8aa3b, v158
	v_exp_f32_e32 v143, v143
	v_lshlrev_b32_e32 v161, 16, v152
	v_and_b32_e32 v152, 0xffff0000, v152
	v_lshlrev_b32_e32 v162, 16, v153
	v_add_f32_e32 v143, 1.0, v143
	v_rcp_f32_e32 v151, v143
	v_mul_f32_e32 v143, 0xbfb8aa3b, v159
	v_exp_f32_e32 v143, v143
	v_and_b32_e32 v153, 0xffff0000, v153
	v_pk_mul_f32 v[126:127], v[126:127], v[150:151]
	v_add_f32_e32 v143, 1.0, v143
	v_rcp_f32_e32 v150, v143
	v_mul_f32_e32 v143, 0xbfb8aa3b, v160
	v_exp_f32_e32 v143, v143
	s_nop 0
	v_add_f32_e32 v143, 1.0, v143
	v_rcp_f32_e32 v151, v143
	v_mul_f32_e32 v143, 0xbfb8aa3b, v161
	v_exp_f32_e32 v143, v143
	v_pk_mul_f32 v[128:129], v[128:129], v[150:151]
	v_add_f32_e32 v143, 1.0, v143
	v_rcp_f32_e32 v150, v143
	v_mul_f32_e32 v143, 0xbfb8aa3b, v152
	v_exp_f32_e32 v143, v143
	s_nop 0
	v_add_f32_e32 v143, 1.0, v143
	v_rcp_f32_e32 v151, v143
	s_nop 0
	v_pk_mul_f32 v[150:151], v[122:123], v[150:151]
	v_mul_f32_e32 v122, 0xbfb8aa3b, v162
	v_mul_f32_e32 v123, 0xbfb8aa3b, v153
	v_exp_f32_e32 v122, v122
	v_exp_f32_e32 v123, v123
	v_add_f32_e32 v122, 1.0, v122
	v_add_f32_e32 v123, 1.0, v123
	v_rcp_f32_e32 v122, v122
	v_rcp_f32_e32 v123, v123
	s_nop 0
	v_pk_mul_f32 v[152:153], v[124:125], v[122:123]
	v_cvt_pk_bf16_f32 v122, v126, v127
	v_cvt_pk_bf16_f32 v123, v128, v129
	v_cvt_pk_bf16_f32 v124, v150, v151
	v_cvt_pk_bf16_f32 v125, v152, v153
	flat_store_dwordx4 v[154:155], v[122:125]
	s_nop 1
	v_mov_b32_e32 v122, v164
	v_mov_b32_e32 v123, v165
	v_mov_b32_e32 v124, v166
	v_mov_b32_e32 v125, v167
	s_nop 0
	v_lshlrev_b32_e32 v126, 16, v122
	v_and_b32_e32 v127, 0xffff0000, v122
	v_lshlrev_b32_e32 v128, 16, v123
	v_and_b32_e32 v129, 0xffff0000, v123
	v_mul_f32_e32 v122, 0xbfb8aa3b, v126
	v_mul_f32_e32 v123, 0xbfb8aa3b, v127
	v_exp_f32_e32 v122, v122
	v_exp_f32_e32 v123, v123
	v_lshlrev_b32_e32 v143, 16, v124
	v_and_b32_e32 v124, 0xffff0000, v124
	v_add_f32_e32 v122, 1.0, v122
	v_add_f32_e32 v123, 1.0, v123
	v_rcp_f32_e32 v122, v122
	v_rcp_f32_e32 v123, v123
	v_lshlrev_b32_e32 v150, 16, v125
	v_and_b32_e32 v125, 0xffff0000, v125
	v_pk_mul_f32 v[118:119], v[118:119], v[122:123]
	v_mul_f32_e32 v122, 0xbfb8aa3b, v128
	v_mul_f32_e32 v123, 0xbfb8aa3b, v129
	v_exp_f32_e32 v122, v122
	v_exp_f32_e32 v123, v123
	v_add_f32_e32 v122, 1.0, v122
	v_add_f32_e32 v123, 1.0, v123
	v_rcp_f32_e32 v122, v122
	v_rcp_f32_e32 v123, v123
	s_nop 0
	v_pk_mul_f32 v[120:121], v[120:121], v[122:123]
	v_mul_f32_e32 v122, 0xbfb8aa3b, v143
	v_mul_f32_e32 v123, 0xbfb8aa3b, v124
	v_exp_f32_e32 v122, v122
	v_exp_f32_e32 v123, v123
	v_add_f32_e32 v122, 1.0, v122
	v_add_f32_e32 v123, 1.0, v123
	v_rcp_f32_e32 v122, v122
	v_rcp_f32_e32 v123, v123
	s_nop 0
	v_pk_mul_f32 v[122:123], v[114:115], v[122:123]
	v_mul_f32_e32 v114, 0xbfb8aa3b, v150
	v_mul_f32_e32 v115, 0xbfb8aa3b, v125
	v_exp_f32_e32 v114, v114
	v_exp_f32_e32 v115, v115
	v_add_f32_e32 v114, 1.0, v114
	v_add_f32_e32 v115, 1.0, v115
	v_rcp_f32_e32 v114, v114
	v_rcp_f32_e32 v115, v115
	s_nop 0
	v_pk_mul_f32 v[124:125], v[116:117], v[114:115]
	v_cvt_pk_bf16_f32 v114, v118, v119
	v_cvt_pk_bf16_f32 v115, v120, v121
	v_cvt_pk_bf16_f32 v116, v122, v123
	v_cvt_pk_bf16_f32 v117, v124, v125
	flat_store_dwordx4 v[154:155], v[114:117] offset:256
	s_nop 1
	v_add_u32_e32 v114, 16, v142
	v_ashrrev_i32_e32 v115, 31, v114
	v_mad_i64_i32 v[118:119], s[28:29], v114, s95, v[144:145]
	v_lshlrev_b64 v[114:115], 11, v[114:115]
	v_lshl_add_u64 v[118:119], v[118:119], 0, v[140:141]
	v_lshl_add_u64 v[116:117], s[26:27], 0, v[114:115]
	v_lshl_add_u64 v[114:115], v[118:119], 0, s[46:47]
	v_add_co_u32_e32 v118, vcc, s16, v118
	v_lshl_add_u64 v[116:117], v[116:117], 0, v[140:141]
	s_nop 0
	v_addc_co_u32_e32 v119, vcc, 0, v119, vcc
	s_nop 1
	v_mov_b32_e32 v118, v168
	v_mov_b32_e32 v119, v169
	v_mov_b32_e32 v120, v170
	v_mov_b32_e32 v121, v171
	s_nop 0
	v_lshlrev_b32_e32 v122, 16, v118
	v_and_b32_e32 v123, 0xffff0000, v118
	v_lshlrev_b32_e32 v124, 16, v119
	v_and_b32_e32 v125, 0xffff0000, v119
	v_mul_f32_e32 v118, 0xbfb8aa3b, v122
	v_mul_f32_e32 v119, 0xbfb8aa3b, v123
	v_exp_f32_e32 v118, v118
	v_exp_f32_e32 v119, v119
	v_lshlrev_b32_e32 v126, 16, v120
	v_and_b32_e32 v120, 0xffff0000, v120
	v_add_f32_e32 v118, 1.0, v118
	v_add_f32_e32 v119, 1.0, v119
	v_rcp_f32_e32 v118, v118
	v_rcp_f32_e32 v119, v119
	v_lshlrev_b32_e32 v127, 16, v121
	v_and_b32_e32 v121, 0xffff0000, v121
	v_pk_mul_f32 v[110:111], v[110:111], v[118:119]
	v_mul_f32_e32 v118, 0xbfb8aa3b, v124
	v_mul_f32_e32 v119, 0xbfb8aa3b, v125
	v_exp_f32_e32 v118, v118
	v_exp_f32_e32 v119, v119
	v_cvt_pk_bf16_f32 v110, v110, v111
	v_add_f32_e32 v118, 1.0, v118
	v_add_f32_e32 v119, 1.0, v119
	v_rcp_f32_e32 v118, v118
	v_rcp_f32_e32 v119, v119
	s_nop 0
	v_pk_mul_f32 v[112:113], v[112:113], v[118:119]
	v_mul_f32_e32 v118, 0xbfb8aa3b, v126
	v_mul_f32_e32 v119, 0xbfb8aa3b, v120
	v_exp_f32_e32 v118, v118
	v_exp_f32_e32 v119, v119
	v_cvt_pk_bf16_f32 v111, v112, v113
	v_add_f32_e32 v118, 1.0, v118
	v_add_f32_e32 v119, 1.0, v119
	v_rcp_f32_e32 v118, v118
	v_rcp_f32_e32 v119, v119
	s_nop 0
	v_pk_mul_f32 v[106:107], v[106:107], v[118:119]
	v_mul_f32_e32 v118, 0xbfb8aa3b, v127
	v_mul_f32_e32 v119, 0xbfb8aa3b, v121
	v_exp_f32_e32 v118, v118
	v_exp_f32_e32 v119, v119
	v_cvt_pk_bf16_f32 v112, v106, v107
	v_add_f32_e32 v118, 1.0, v118
	v_add_f32_e32 v119, 1.0, v119
	v_rcp_f32_e32 v118, v118
	v_rcp_f32_e32 v119, v119
	s_nop 0
	v_pk_mul_f32 v[108:109], v[108:109], v[118:119]
	s_nop 0
	v_cvt_pk_bf16_f32 v113, v108, v109
	flat_store_dwordx4 v[116:117], v[110:113]
	s_nop 1
	v_mov_b32_e32 v106, v172
	v_mov_b32_e32 v107, v173
	v_mov_b32_e32 v108, v174
	v_mov_b32_e32 v109, v175
	s_nop 0
	v_lshlrev_b32_e32 v114, 16, v108
	v_lshlrev_b32_e32 v110, 16, v106
	v_and_b32_e32 v111, 0xffff0000, v106
	v_lshlrev_b32_e32 v112, 16, v107
	v_and_b32_e32 v113, 0xffff0000, v107
	v_mul_f32_e32 v106, 0xbfb8aa3b, v110
	v_mul_f32_e32 v107, 0xbfb8aa3b, v111
	v_exp_f32_e32 v106, v106
	v_exp_f32_e32 v107, v107
	v_and_b32_e32 v108, 0xffff0000, v108
	v_lshlrev_b32_e32 v115, 16, v109
	v_add_f32_e32 v106, 1.0, v106
	v_add_f32_e32 v107, 1.0, v107
	v_rcp_f32_e32 v106, v106
	v_rcp_f32_e32 v107, v107
	v_and_b32_e32 v109, 0xffff0000, v109
	v_pk_mul_f32 v[102:103], v[102:103], v[106:107]
	v_mul_f32_e32 v106, 0xbfb8aa3b, v112
	v_mul_f32_e32 v107, 0xbfb8aa3b, v113
	v_exp_f32_e32 v106, v106
	v_exp_f32_e32 v107, v107
	v_add_f32_e32 v106, 1.0, v106
	v_add_f32_e32 v107, 1.0, v107
	v_rcp_f32_e32 v106, v106
	v_rcp_f32_e32 v107, v107
	s_nop 0
	v_pk_mul_f32 v[104:105], v[104:105], v[106:107]
	v_mul_f32_e32 v106, 0xbfb8aa3b, v114
	v_mul_f32_e32 v107, 0xbfb8aa3b, v108
	v_exp_f32_e32 v106, v106
	v_exp_f32_e32 v107, v107
	v_add_f32_e32 v106, 1.0, v106
	v_add_f32_e32 v107, 1.0, v107
	v_rcp_f32_e32 v106, v106
	v_rcp_f32_e32 v107, v107
	s_nop 0
	v_pk_mul_f32 v[106:107], v[98:99], v[106:107]
	v_mul_f32_e32 v98, 0xbfb8aa3b, v115
	v_mul_f32_e32 v99, 0xbfb8aa3b, v109
	v_exp_f32_e32 v98, v98
	v_exp_f32_e32 v99, v99
	v_add_f32_e32 v98, 1.0, v98
	v_add_f32_e32 v99, 1.0, v99
	v_rcp_f32_e32 v98, v98
	v_rcp_f32_e32 v99, v99
	s_nop 0
	v_pk_mul_f32 v[108:109], v[100:101], v[98:99]
	v_cvt_pk_bf16_f32 v98, v102, v103
	v_cvt_pk_bf16_f32 v99, v104, v105
	v_cvt_pk_bf16_f32 v100, v106, v107
	v_cvt_pk_bf16_f32 v101, v108, v109
	flat_store_dwordx4 v[116:117], v[98:101] offset:256
	s_nop 1
	v_add_u32_e32 v98, 32, v142
	v_ashrrev_i32_e32 v99, 31, v98
	v_mad_i64_i32 v[102:103], s[28:29], v98, s95, v[144:145]
	v_lshlrev_b64 v[98:99], 11, v[98:99]
	v_lshl_add_u64 v[102:103], v[102:103], 0, v[140:141]
	v_lshl_add_u64 v[100:101], s[26:27], 0, v[98:99]
	v_lshl_add_u64 v[98:99], v[102:103], 0, s[46:47]
	v_add_co_u32_e32 v102, vcc, s16, v102
	v_lshl_add_u64 v[100:101], v[100:101], 0, v[140:141]
	s_nop 0
	v_addc_co_u32_e32 v103, vcc, 0, v103, vcc
	s_nop 1
	v_mov_b32_e32 v102, v176
	v_mov_b32_e32 v103, v177
	v_mov_b32_e32 v104, v178
	v_mov_b32_e32 v105, v179
	s_nop 0
	v_lshlrev_b32_e32 v106, 16, v102
	v_and_b32_e32 v107, 0xffff0000, v102
	v_lshlrev_b32_e32 v108, 16, v103
	v_and_b32_e32 v109, 0xffff0000, v103
	v_mul_f32_e32 v102, 0xbfb8aa3b, v106
	v_mul_f32_e32 v103, 0xbfb8aa3b, v107
	v_exp_f32_e32 v102, v102
	v_exp_f32_e32 v103, v103
	v_lshlrev_b32_e32 v110, 16, v104
	v_and_b32_e32 v104, 0xffff0000, v104
	v_add_f32_e32 v102, 1.0, v102
	v_add_f32_e32 v103, 1.0, v103
	v_rcp_f32_e32 v102, v102
	v_rcp_f32_e32 v103, v103
	v_lshlrev_b32_e32 v111, 16, v105
	v_and_b32_e32 v105, 0xffff0000, v105
	v_pk_mul_f32 v[94:95], v[94:95], v[102:103]
	v_mul_f32_e32 v102, 0xbfb8aa3b, v108
	v_mul_f32_e32 v103, 0xbfb8aa3b, v109
	v_exp_f32_e32 v102, v102
	v_exp_f32_e32 v103, v103
	v_cvt_pk_bf16_f32 v94, v94, v95
	v_add_f32_e32 v102, 1.0, v102
	v_add_f32_e32 v103, 1.0, v103
	v_rcp_f32_e32 v102, v102
	v_rcp_f32_e32 v103, v103
	s_nop 0
	v_pk_mul_f32 v[96:97], v[96:97], v[102:103]
	v_mul_f32_e32 v102, 0xbfb8aa3b, v110
	v_mul_f32_e32 v103, 0xbfb8aa3b, v104
	v_exp_f32_e32 v102, v102
	v_exp_f32_e32 v103, v103
	v_cvt_pk_bf16_f32 v95, v96, v97
	v_add_f32_e32 v102, 1.0, v102
	v_add_f32_e32 v103, 1.0, v103
	v_rcp_f32_e32 v102, v102
	v_rcp_f32_e32 v103, v103
	s_nop 0
	v_pk_mul_f32 v[90:91], v[90:91], v[102:103]
	v_mul_f32_e32 v102, 0xbfb8aa3b, v111
	v_mul_f32_e32 v103, 0xbfb8aa3b, v105
	v_exp_f32_e32 v102, v102
	v_exp_f32_e32 v103, v103
	v_cvt_pk_bf16_f32 v96, v90, v91
	v_add_f32_e32 v102, 1.0, v102
	v_add_f32_e32 v103, 1.0, v103
	v_rcp_f32_e32 v102, v102
	v_rcp_f32_e32 v103, v103
	s_nop 0
	v_pk_mul_f32 v[92:93], v[92:93], v[102:103]
	s_nop 0
	v_cvt_pk_bf16_f32 v97, v92, v93
	flat_store_dwordx4 v[100:101], v[94:97]
	s_nop 1
	v_mov_b32_e32 v90, v182
	v_mov_b32_e32 v91, v183
	v_mov_b32_e32 v92, v184
	v_mov_b32_e32 v93, v185
	s_nop 0
	v_lshlrev_b32_e32 v98, 16, v92
	v_lshlrev_b32_e32 v94, 16, v90
	v_and_b32_e32 v95, 0xffff0000, v90
	v_lshlrev_b32_e32 v96, 16, v91
	v_and_b32_e32 v97, 0xffff0000, v91
	v_mul_f32_e32 v90, 0xbfb8aa3b, v94
	v_mul_f32_e32 v91, 0xbfb8aa3b, v95
	v_exp_f32_e32 v90, v90
	v_exp_f32_e32 v91, v91
	v_and_b32_e32 v92, 0xffff0000, v92
	v_lshlrev_b32_e32 v99, 16, v93
	v_add_f32_e32 v90, 1.0, v90
	v_add_f32_e32 v91, 1.0, v91
	v_rcp_f32_e32 v90, v90
	v_rcp_f32_e32 v91, v91
	v_and_b32_e32 v93, 0xffff0000, v93
	v_pk_mul_f32 v[86:87], v[86:87], v[90:91]
	v_mul_f32_e32 v90, 0xbfb8aa3b, v96
	v_mul_f32_e32 v91, 0xbfb8aa3b, v97
	v_exp_f32_e32 v90, v90
	v_exp_f32_e32 v91, v91
	v_add_f32_e32 v90, 1.0, v90
	v_add_f32_e32 v91, 1.0, v91
	v_rcp_f32_e32 v90, v90
	v_rcp_f32_e32 v91, v91
	s_nop 0
	v_pk_mul_f32 v[88:89], v[88:89], v[90:91]
	v_mul_f32_e32 v90, 0xbfb8aa3b, v98
	v_mul_f32_e32 v91, 0xbfb8aa3b, v92
	v_exp_f32_e32 v90, v90
	v_exp_f32_e32 v91, v91
	v_add_f32_e32 v90, 1.0, v90
	v_add_f32_e32 v91, 1.0, v91
	v_rcp_f32_e32 v90, v90
	v_rcp_f32_e32 v91, v91
	s_nop 0
	v_pk_mul_f32 v[90:91], v[82:83], v[90:91]
	v_mul_f32_e32 v82, 0xbfb8aa3b, v99
	v_mul_f32_e32 v83, 0xbfb8aa3b, v93
	v_exp_f32_e32 v82, v82
	v_exp_f32_e32 v83, v83
	v_add_f32_e32 v82, 1.0, v82
	v_add_f32_e32 v83, 1.0, v83
	v_rcp_f32_e32 v82, v82
	v_rcp_f32_e32 v83, v83
	s_nop 0
	v_pk_mul_f32 v[92:93], v[84:85], v[82:83]
	v_cvt_pk_bf16_f32 v82, v86, v87
	v_cvt_pk_bf16_f32 v83, v88, v89
	v_cvt_pk_bf16_f32 v84, v90, v91
	v_cvt_pk_bf16_f32 v85, v92, v93
	flat_store_dwordx4 v[100:101], v[82:85] offset:256
	s_nop 1
	v_add_u32_e32 v82, 48, v142
	v_ashrrev_i32_e32 v83, 31, v82
	v_mad_i64_i32 v[86:87], s[28:29], v82, s95, v[144:145]
	v_lshlrev_b64 v[82:83], 11, v[82:83]
	v_lshl_add_u64 v[86:87], v[86:87], 0, v[140:141]
	v_lshl_add_u64 v[84:85], s[26:27], 0, v[82:83]
	v_lshl_add_u64 v[82:83], v[86:87], 0, s[46:47]
	v_add_co_u32_e32 v86, vcc, s16, v86
	v_lshl_add_u64 v[84:85], v[84:85], 0, v[140:141]
	s_nop 0
	v_addc_co_u32_e32 v87, vcc, 0, v87, vcc
	s_nop 1
	v_mov_b32_e32 v86, v186
	v_mov_b32_e32 v87, v187
	v_mov_b32_e32 v88, v188
	v_mov_b32_e32 v89, v189
	s_nop 0
	v_lshlrev_b32_e32 v90, 16, v86
	v_and_b32_e32 v91, 0xffff0000, v86
	v_lshlrev_b32_e32 v92, 16, v87
	v_and_b32_e32 v93, 0xffff0000, v87
	v_mul_f32_e32 v86, 0xbfb8aa3b, v90
	v_mul_f32_e32 v87, 0xbfb8aa3b, v91
	v_exp_f32_e32 v86, v86
	v_exp_f32_e32 v87, v87
	v_lshlrev_b32_e32 v94, 16, v88
	v_and_b32_e32 v88, 0xffff0000, v88
	v_add_f32_e32 v86, 1.0, v86
	v_add_f32_e32 v87, 1.0, v87
	v_rcp_f32_e32 v86, v86
	v_rcp_f32_e32 v87, v87
	v_lshlrev_b32_e32 v95, 16, v89
	v_and_b32_e32 v89, 0xffff0000, v89
	v_pk_mul_f32 v[78:79], v[78:79], v[86:87]
	v_mul_f32_e32 v86, 0xbfb8aa3b, v92
	v_mul_f32_e32 v87, 0xbfb8aa3b, v93
	v_exp_f32_e32 v86, v86
	v_exp_f32_e32 v87, v87
	v_cvt_pk_bf16_f32 v78, v78, v79
	v_add_f32_e32 v86, 1.0, v86
	v_add_f32_e32 v87, 1.0, v87
	v_rcp_f32_e32 v86, v86
	v_rcp_f32_e32 v87, v87
	s_nop 0
	v_pk_mul_f32 v[80:81], v[80:81], v[86:87]
	v_mul_f32_e32 v86, 0xbfb8aa3b, v94
	v_mul_f32_e32 v87, 0xbfb8aa3b, v88
	v_exp_f32_e32 v86, v86
	v_exp_f32_e32 v87, v87
	v_cvt_pk_bf16_f32 v79, v80, v81
	v_add_f32_e32 v86, 1.0, v86
	v_add_f32_e32 v87, 1.0, v87
	v_rcp_f32_e32 v86, v86
	v_rcp_f32_e32 v87, v87
	s_nop 0
	v_pk_mul_f32 v[74:75], v[74:75], v[86:87]
	v_mul_f32_e32 v86, 0xbfb8aa3b, v95
	v_mul_f32_e32 v87, 0xbfb8aa3b, v89
	v_exp_f32_e32 v86, v86
	v_exp_f32_e32 v87, v87
	v_cvt_pk_bf16_f32 v80, v74, v75
	v_add_f32_e32 v86, 1.0, v86
	v_add_f32_e32 v87, 1.0, v87
	v_rcp_f32_e32 v86, v86
	v_rcp_f32_e32 v87, v87
	s_nop 0
	v_pk_mul_f32 v[76:77], v[76:77], v[86:87]
	s_nop 0
	v_cvt_pk_bf16_f32 v81, v76, v77
	flat_store_dwordx4 v[84:85], v[78:81]
	s_nop 1
	v_mov_b32_e32 v74, v190
	v_mov_b32_e32 v75, v191
	v_mov_b32_e32 v76, v192
	v_mov_b32_e32 v77, v193
	s_nop 0
	v_lshlrev_b32_e32 v82, 16, v76
	v_lshlrev_b32_e32 v78, 16, v74
	v_and_b32_e32 v79, 0xffff0000, v74
	v_lshlrev_b32_e32 v80, 16, v75
	v_and_b32_e32 v81, 0xffff0000, v75
	v_mul_f32_e32 v74, 0xbfb8aa3b, v78
	v_mul_f32_e32 v75, 0xbfb8aa3b, v79
	v_exp_f32_e32 v74, v74
	v_exp_f32_e32 v75, v75
	v_and_b32_e32 v76, 0xffff0000, v76
	v_lshlrev_b32_e32 v83, 16, v77
	v_add_f32_e32 v74, 1.0, v74
	v_add_f32_e32 v75, 1.0, v75
	v_rcp_f32_e32 v74, v74
	v_rcp_f32_e32 v75, v75
	v_and_b32_e32 v77, 0xffff0000, v77
	v_pk_mul_f32 v[70:71], v[70:71], v[74:75]
	v_mul_f32_e32 v74, 0xbfb8aa3b, v80
	v_mul_f32_e32 v75, 0xbfb8aa3b, v81
	v_exp_f32_e32 v74, v74
	v_exp_f32_e32 v75, v75
	v_add_f32_e32 v74, 1.0, v74
	v_add_f32_e32 v75, 1.0, v75
	v_rcp_f32_e32 v74, v74
	v_rcp_f32_e32 v75, v75
	s_nop 0
	v_pk_mul_f32 v[72:73], v[72:73], v[74:75]
	v_mul_f32_e32 v74, 0xbfb8aa3b, v82
	v_mul_f32_e32 v75, 0xbfb8aa3b, v76
	v_exp_f32_e32 v74, v74
	v_exp_f32_e32 v75, v75
	v_add_f32_e32 v74, 1.0, v74
	v_add_f32_e32 v75, 1.0, v75
	v_rcp_f32_e32 v74, v74
	v_rcp_f32_e32 v75, v75
	s_nop 0
	v_pk_mul_f32 v[74:75], v[66:67], v[74:75]
	v_mul_f32_e32 v66, 0xbfb8aa3b, v83
	v_mul_f32_e32 v67, 0xbfb8aa3b, v77
	v_exp_f32_e32 v66, v66
	v_exp_f32_e32 v67, v67
	v_add_f32_e32 v66, 1.0, v66
	v_add_f32_e32 v67, 1.0, v67
	v_rcp_f32_e32 v66, v66
	v_rcp_f32_e32 v67, v67
	s_nop 0
	v_pk_mul_f32 v[76:77], v[68:69], v[66:67]
	v_cvt_pk_bf16_f32 v66, v70, v71
	v_cvt_pk_bf16_f32 v67, v72, v73
	v_cvt_pk_bf16_f32 v68, v74, v75
	v_cvt_pk_bf16_f32 v69, v76, v77
	flat_store_dwordx4 v[84:85], v[66:69] offset:256
	s_nop 1
	v_add_u32_e32 v66, 0x80, v142
	v_ashrrev_i32_e32 v67, 31, v66
	v_mad_i64_i32 v[70:71], s[28:29], v66, s95, v[144:145]
	v_lshlrev_b64 v[66:67], 11, v[66:67]
	v_lshl_add_u64 v[70:71], v[70:71], 0, v[140:141]
	v_lshl_add_u64 v[68:69], s[26:27], 0, v[66:67]
	v_lshl_add_u64 v[66:67], v[70:71], 0, s[46:47]
	v_add_co_u32_e32 v70, vcc, s16, v70
	v_lshl_add_u64 v[68:69], v[68:69], 0, v[140:141]
	s_nop 0
	v_addc_co_u32_e32 v71, vcc, 0, v71, vcc
	s_nop 1
	v_mov_b32_e32 v70, v194
	v_mov_b32_e32 v71, v195
	v_mov_b32_e32 v72, v196
	v_mov_b32_e32 v73, v197
	s_nop 0
	v_lshlrev_b32_e32 v74, 16, v70
	v_and_b32_e32 v75, 0xffff0000, v70
	v_lshlrev_b32_e32 v76, 16, v71
	v_and_b32_e32 v77, 0xffff0000, v71
	v_mul_f32_e32 v70, 0xbfb8aa3b, v74
	v_mul_f32_e32 v71, 0xbfb8aa3b, v75
	v_exp_f32_e32 v70, v70
	v_exp_f32_e32 v71, v71
	v_lshlrev_b32_e32 v78, 16, v72
	v_and_b32_e32 v72, 0xffff0000, v72
	v_add_f32_e32 v70, 1.0, v70
	v_add_f32_e32 v71, 1.0, v71
	v_rcp_f32_e32 v70, v70
	v_rcp_f32_e32 v71, v71
	v_lshlrev_b32_e32 v79, 16, v73
	v_and_b32_e32 v73, 0xffff0000, v73
	v_pk_mul_f32 v[62:63], v[62:63], v[70:71]
	v_mul_f32_e32 v70, 0xbfb8aa3b, v76
	v_mul_f32_e32 v71, 0xbfb8aa3b, v77
	v_exp_f32_e32 v70, v70
	v_exp_f32_e32 v71, v71
	v_cvt_pk_bf16_f32 v62, v62, v63
	v_add_f32_e32 v70, 1.0, v70
	v_add_f32_e32 v71, 1.0, v71
	v_rcp_f32_e32 v70, v70
	v_rcp_f32_e32 v71, v71
	s_nop 0
	v_pk_mul_f32 v[64:65], v[64:65], v[70:71]
	v_mul_f32_e32 v70, 0xbfb8aa3b, v78
	v_mul_f32_e32 v71, 0xbfb8aa3b, v72
	v_exp_f32_e32 v70, v70
	v_exp_f32_e32 v71, v71
	v_cvt_pk_bf16_f32 v63, v64, v65
	v_add_f32_e32 v70, 1.0, v70
	v_add_f32_e32 v71, 1.0, v71
	v_rcp_f32_e32 v70, v70
	v_rcp_f32_e32 v71, v71
	s_nop 0
	v_pk_mul_f32 v[58:59], v[58:59], v[70:71]
	v_mul_f32_e32 v70, 0xbfb8aa3b, v79
	v_mul_f32_e32 v71, 0xbfb8aa3b, v73
	v_exp_f32_e32 v70, v70
	v_exp_f32_e32 v71, v71
	v_cvt_pk_bf16_f32 v64, v58, v59
	v_add_f32_e32 v70, 1.0, v70
	v_add_f32_e32 v71, 1.0, v71
	v_rcp_f32_e32 v70, v70
	v_rcp_f32_e32 v71, v71
	s_nop 0
	v_pk_mul_f32 v[60:61], v[60:61], v[70:71]
	s_nop 0
	v_cvt_pk_bf16_f32 v65, v60, v61
	flat_store_dwordx4 v[68:69], v[62:65]
	s_nop 1
	v_mov_b32_e32 v58, v218
	v_mov_b32_e32 v59, v219
	v_mov_b32_e32 v60, v220
	v_mov_b32_e32 v61, v221
	s_nop 0
	v_lshlrev_b32_e32 v66, 16, v60
	v_lshlrev_b32_e32 v62, 16, v58
	v_and_b32_e32 v63, 0xffff0000, v58
	v_lshlrev_b32_e32 v64, 16, v59
	v_and_b32_e32 v65, 0xffff0000, v59
	v_mul_f32_e32 v58, 0xbfb8aa3b, v62
	v_mul_f32_e32 v59, 0xbfb8aa3b, v63
	v_exp_f32_e32 v58, v58
	v_exp_f32_e32 v59, v59
	v_and_b32_e32 v60, 0xffff0000, v60
	v_lshlrev_b32_e32 v67, 16, v61
	v_add_f32_e32 v58, 1.0, v58
	v_add_f32_e32 v59, 1.0, v59
	v_rcp_f32_e32 v58, v58
	v_rcp_f32_e32 v59, v59
	v_and_b32_e32 v61, 0xffff0000, v61
	v_pk_mul_f32 v[54:55], v[54:55], v[58:59]
	v_mul_f32_e32 v58, 0xbfb8aa3b, v64
	v_mul_f32_e32 v59, 0xbfb8aa3b, v65
	v_exp_f32_e32 v58, v58
	v_exp_f32_e32 v59, v59
	v_add_f32_e32 v58, 1.0, v58
	v_add_f32_e32 v59, 1.0, v59
	v_rcp_f32_e32 v58, v58
	v_rcp_f32_e32 v59, v59
	s_nop 0
	v_pk_mul_f32 v[56:57], v[56:57], v[58:59]
	v_mul_f32_e32 v58, 0xbfb8aa3b, v66
	v_mul_f32_e32 v59, 0xbfb8aa3b, v60
	v_exp_f32_e32 v58, v58
	v_exp_f32_e32 v59, v59
	v_add_f32_e32 v58, 1.0, v58
	v_add_f32_e32 v59, 1.0, v59
	v_rcp_f32_e32 v58, v58
	v_rcp_f32_e32 v59, v59
	s_nop 0
	v_pk_mul_f32 v[58:59], v[50:51], v[58:59]
	v_mul_f32_e32 v50, 0xbfb8aa3b, v67
	v_mul_f32_e32 v51, 0xbfb8aa3b, v61
	v_exp_f32_e32 v50, v50
	v_exp_f32_e32 v51, v51
	v_add_f32_e32 v50, 1.0, v50
	v_add_f32_e32 v51, 1.0, v51
	v_rcp_f32_e32 v50, v50
	v_rcp_f32_e32 v51, v51
	s_nop 0
	v_pk_mul_f32 v[60:61], v[52:53], v[50:51]
	v_cvt_pk_bf16_f32 v50, v54, v55
	v_cvt_pk_bf16_f32 v51, v56, v57
	v_cvt_pk_bf16_f32 v52, v58, v59
	v_cvt_pk_bf16_f32 v53, v60, v61
	flat_store_dwordx4 v[68:69], v[50:53] offset:256
	s_nop 1
	v_add_u32_e32 v50, 0x90, v142
	v_ashrrev_i32_e32 v51, 31, v50
	v_mad_i64_i32 v[54:55], s[28:29], v50, s95, v[144:145]
	v_lshlrev_b64 v[50:51], 11, v[50:51]
	v_lshl_add_u64 v[54:55], v[54:55], 0, v[140:141]
	v_lshl_add_u64 v[52:53], s[26:27], 0, v[50:51]
	v_lshl_add_u64 v[50:51], v[54:55], 0, s[46:47]
	v_add_co_u32_e32 v54, vcc, s16, v54
	v_lshl_add_u64 v[52:53], v[52:53], 0, v[140:141]
	s_nop 0
	v_addc_co_u32_e32 v55, vcc, 0, v55, vcc
	s_nop 1
	v_mov_b32_e32 v54, v222
	v_mov_b32_e32 v55, v223
	v_mov_b32_e32 v56, v224
	v_mov_b32_e32 v57, v225
	s_nop 0
	v_lshlrev_b32_e32 v58, 16, v54
	v_and_b32_e32 v59, 0xffff0000, v54
	v_lshlrev_b32_e32 v60, 16, v55
	v_and_b32_e32 v61, 0xffff0000, v55
	v_mul_f32_e32 v54, 0xbfb8aa3b, v58
	v_mul_f32_e32 v55, 0xbfb8aa3b, v59
	v_exp_f32_e32 v54, v54
	v_exp_f32_e32 v55, v55
	v_lshlrev_b32_e32 v62, 16, v56
	v_and_b32_e32 v56, 0xffff0000, v56
	v_add_f32_e32 v54, 1.0, v54
	v_add_f32_e32 v55, 1.0, v55
	v_rcp_f32_e32 v54, v54
	v_rcp_f32_e32 v55, v55
	v_lshlrev_b32_e32 v63, 16, v57
	v_and_b32_e32 v57, 0xffff0000, v57
	v_pk_mul_f32 v[46:47], v[46:47], v[54:55]
	v_mul_f32_e32 v54, 0xbfb8aa3b, v60
	v_mul_f32_e32 v55, 0xbfb8aa3b, v61
	v_exp_f32_e32 v54, v54
	v_exp_f32_e32 v55, v55
	v_cvt_pk_bf16_f32 v46, v46, v47
	v_add_f32_e32 v54, 1.0, v54
	v_add_f32_e32 v55, 1.0, v55
	v_rcp_f32_e32 v54, v54
	v_rcp_f32_e32 v55, v55
	s_nop 0
	v_pk_mul_f32 v[48:49], v[48:49], v[54:55]
	v_mul_f32_e32 v54, 0xbfb8aa3b, v62
	v_mul_f32_e32 v55, 0xbfb8aa3b, v56
	v_exp_f32_e32 v54, v54
	v_exp_f32_e32 v55, v55
	v_cvt_pk_bf16_f32 v47, v48, v49
	v_add_f32_e32 v54, 1.0, v54
	v_add_f32_e32 v55, 1.0, v55
	v_rcp_f32_e32 v54, v54
	v_rcp_f32_e32 v55, v55
	s_nop 0
	v_pk_mul_f32 v[42:43], v[42:43], v[54:55]
	v_mul_f32_e32 v54, 0xbfb8aa3b, v63
	v_mul_f32_e32 v55, 0xbfb8aa3b, v57
	v_exp_f32_e32 v54, v54
	v_exp_f32_e32 v55, v55
	v_cvt_pk_bf16_f32 v48, v42, v43
	v_add_f32_e32 v54, 1.0, v54
	v_add_f32_e32 v55, 1.0, v55
	v_rcp_f32_e32 v54, v54
	v_rcp_f32_e32 v55, v55
	s_nop 0
	v_pk_mul_f32 v[44:45], v[44:45], v[54:55]
	s_nop 0
	v_cvt_pk_bf16_f32 v49, v44, v45
	flat_store_dwordx4 v[52:53], v[46:49]
	s_nop 1
	v_mov_b32_e32 v42, v230
	v_mov_b32_e32 v43, v231
	v_mov_b32_e32 v44, v232
	v_mov_b32_e32 v45, v233
	s_nop 0
	v_lshlrev_b32_e32 v50, 16, v44
	v_lshlrev_b32_e32 v46, 16, v42
	v_and_b32_e32 v47, 0xffff0000, v42
	v_lshlrev_b32_e32 v48, 16, v43
	v_and_b32_e32 v49, 0xffff0000, v43
	v_mul_f32_e32 v42, 0xbfb8aa3b, v46
	v_mul_f32_e32 v43, 0xbfb8aa3b, v47
	v_exp_f32_e32 v42, v42
	v_exp_f32_e32 v43, v43
	v_and_b32_e32 v44, 0xffff0000, v44
	v_lshlrev_b32_e32 v51, 16, v45
	v_add_f32_e32 v42, 1.0, v42
	v_add_f32_e32 v43, 1.0, v43
	v_rcp_f32_e32 v42, v42
	v_rcp_f32_e32 v43, v43
	v_and_b32_e32 v45, 0xffff0000, v45
	v_pk_mul_f32 v[38:39], v[38:39], v[42:43]
	v_mul_f32_e32 v42, 0xbfb8aa3b, v48
	v_mul_f32_e32 v43, 0xbfb8aa3b, v49
	v_exp_f32_e32 v42, v42
	v_exp_f32_e32 v43, v43
	v_add_f32_e32 v42, 1.0, v42
	v_add_f32_e32 v43, 1.0, v43
	v_rcp_f32_e32 v42, v42
	v_rcp_f32_e32 v43, v43
	s_nop 0
	v_pk_mul_f32 v[40:41], v[40:41], v[42:43]
	v_mul_f32_e32 v42, 0xbfb8aa3b, v50
	v_mul_f32_e32 v43, 0xbfb8aa3b, v44
	v_exp_f32_e32 v42, v42
	v_exp_f32_e32 v43, v43
	v_add_f32_e32 v42, 1.0, v42
	v_add_f32_e32 v43, 1.0, v43
	v_rcp_f32_e32 v42, v42
	v_rcp_f32_e32 v43, v43
	s_nop 0
	v_pk_mul_f32 v[42:43], v[34:35], v[42:43]
	v_mul_f32_e32 v34, 0xbfb8aa3b, v51
	v_mul_f32_e32 v35, 0xbfb8aa3b, v45
	v_exp_f32_e32 v34, v34
	v_exp_f32_e32 v35, v35
	v_add_f32_e32 v34, 1.0, v34
	v_add_f32_e32 v35, 1.0, v35
	v_rcp_f32_e32 v34, v34
	v_rcp_f32_e32 v35, v35
	s_nop 0
	v_pk_mul_f32 v[44:45], v[36:37], v[34:35]
	v_cvt_pk_bf16_f32 v34, v38, v39
	v_cvt_pk_bf16_f32 v35, v40, v41
	v_cvt_pk_bf16_f32 v36, v42, v43
	v_cvt_pk_bf16_f32 v37, v44, v45
	flat_store_dwordx4 v[52:53], v[34:37] offset:256
	s_nop 1
	v_add_u32_e32 v34, 0xa0, v142
	v_ashrrev_i32_e32 v35, 31, v34
	v_mad_i64_i32 v[38:39], s[28:29], v34, s95, v[144:145]
	v_lshlrev_b64 v[34:35], 11, v[34:35]
	v_lshl_add_u64 v[38:39], v[38:39], 0, v[140:141]
	v_lshl_add_u64 v[36:37], s[26:27], 0, v[34:35]
	v_lshl_add_u64 v[34:35], v[38:39], 0, s[46:47]
	v_add_co_u32_e32 v38, vcc, s16, v38
	v_lshl_add_u64 v[36:37], v[36:37], 0, v[140:141]
	s_nop 0
	v_addc_co_u32_e32 v39, vcc, 0, v39, vcc
	s_nop 1
	v_mov_b32_e32 v38, v234
	v_mov_b32_e32 v39, v235
	v_mov_b32_e32 v40, v236
	v_mov_b32_e32 v41, v237
	s_nop 0
	v_lshlrev_b32_e32 v42, 16, v38
	v_and_b32_e32 v43, 0xffff0000, v38
	v_lshlrev_b32_e32 v44, 16, v39
	v_and_b32_e32 v45, 0xffff0000, v39
	v_mul_f32_e32 v38, 0xbfb8aa3b, v42
	v_mul_f32_e32 v39, 0xbfb8aa3b, v43
	v_exp_f32_e32 v38, v38
	v_exp_f32_e32 v39, v39
	v_lshlrev_b32_e32 v46, 16, v40
	v_and_b32_e32 v40, 0xffff0000, v40
	v_add_f32_e32 v38, 1.0, v38
	v_add_f32_e32 v39, 1.0, v39
	v_rcp_f32_e32 v38, v38
	v_rcp_f32_e32 v39, v39
	v_lshlrev_b32_e32 v47, 16, v41
	v_and_b32_e32 v41, 0xffff0000, v41
	v_pk_mul_f32 v[30:31], v[30:31], v[38:39]
	v_mul_f32_e32 v38, 0xbfb8aa3b, v44
	v_mul_f32_e32 v39, 0xbfb8aa3b, v45
	v_exp_f32_e32 v38, v38
	v_exp_f32_e32 v39, v39
	v_cvt_pk_bf16_f32 v30, v30, v31
	v_add_f32_e32 v38, 1.0, v38
	v_add_f32_e32 v39, 1.0, v39
	v_rcp_f32_e32 v38, v38
	v_rcp_f32_e32 v39, v39
	s_nop 0
	v_pk_mul_f32 v[32:33], v[32:33], v[38:39]
	v_mul_f32_e32 v38, 0xbfb8aa3b, v46
	v_mul_f32_e32 v39, 0xbfb8aa3b, v40
	v_exp_f32_e32 v38, v38
	v_exp_f32_e32 v39, v39
	v_cvt_pk_bf16_f32 v31, v32, v33
	v_add_f32_e32 v38, 1.0, v38
	v_add_f32_e32 v39, 1.0, v39
	v_rcp_f32_e32 v38, v38
	v_rcp_f32_e32 v39, v39
	s_nop 0
	v_pk_mul_f32 v[26:27], v[26:27], v[38:39]
	v_mul_f32_e32 v38, 0xbfb8aa3b, v47
	v_mul_f32_e32 v39, 0xbfb8aa3b, v41
	v_exp_f32_e32 v38, v38
	v_exp_f32_e32 v39, v39
	v_cvt_pk_bf16_f32 v32, v26, v27
	v_add_f32_e32 v38, 1.0, v38
	v_add_f32_e32 v39, 1.0, v39
	v_rcp_f32_e32 v38, v38
	v_rcp_f32_e32 v39, v39
	s_nop 0
	v_pk_mul_f32 v[28:29], v[28:29], v[38:39]
	s_nop 0
	v_cvt_pk_bf16_f32 v33, v28, v29
	flat_store_dwordx4 v[36:37], v[30:33]
	s_nop 1
	v_mov_b32_e32 v26, v238
	v_mov_b32_e32 v27, v239
	v_mov_b32_e32 v28, v240
	v_mov_b32_e32 v29, v241
	s_nop 0
	v_lshlrev_b32_e32 v34, 16, v28
	v_lshlrev_b32_e32 v30, 16, v26
	v_and_b32_e32 v31, 0xffff0000, v26
	v_lshlrev_b32_e32 v32, 16, v27
	v_and_b32_e32 v33, 0xffff0000, v27
	v_mul_f32_e32 v26, 0xbfb8aa3b, v30
	v_mul_f32_e32 v27, 0xbfb8aa3b, v31
	v_exp_f32_e32 v26, v26
	v_exp_f32_e32 v27, v27
	v_and_b32_e32 v28, 0xffff0000, v28
	v_lshlrev_b32_e32 v35, 16, v29
	v_add_f32_e32 v26, 1.0, v26
	v_add_f32_e32 v27, 1.0, v27
	v_rcp_f32_e32 v26, v26
	v_rcp_f32_e32 v27, v27
	v_and_b32_e32 v29, 0xffff0000, v29
	v_pk_mul_f32 v[22:23], v[22:23], v[26:27]
	v_mul_f32_e32 v26, 0xbfb8aa3b, v32
	v_mul_f32_e32 v27, 0xbfb8aa3b, v33
	v_exp_f32_e32 v26, v26
	v_exp_f32_e32 v27, v27
	v_add_f32_e32 v26, 1.0, v26
	v_add_f32_e32 v27, 1.0, v27
	v_rcp_f32_e32 v26, v26
	v_rcp_f32_e32 v27, v27
	s_nop 0
	v_pk_mul_f32 v[24:25], v[24:25], v[26:27]
	v_mul_f32_e32 v26, 0xbfb8aa3b, v34
	v_mul_f32_e32 v27, 0xbfb8aa3b, v28
	v_exp_f32_e32 v26, v26
	v_exp_f32_e32 v27, v27
	v_add_f32_e32 v26, 1.0, v26
	v_add_f32_e32 v27, 1.0, v27
	v_rcp_f32_e32 v26, v26
	v_rcp_f32_e32 v27, v27
	s_nop 0
	v_pk_mul_f32 v[26:27], v[18:19], v[26:27]
	v_mul_f32_e32 v18, 0xbfb8aa3b, v35
	v_mul_f32_e32 v19, 0xbfb8aa3b, v29
	v_exp_f32_e32 v18, v18
	v_exp_f32_e32 v19, v19
	v_add_f32_e32 v18, 1.0, v18
	v_add_f32_e32 v19, 1.0, v19
	v_rcp_f32_e32 v18, v18
	v_rcp_f32_e32 v19, v19
	s_nop 0
	v_pk_mul_f32 v[28:29], v[20:21], v[18:19]
	v_cvt_pk_bf16_f32 v18, v22, v23
	v_cvt_pk_bf16_f32 v19, v24, v25
	v_cvt_pk_bf16_f32 v20, v26, v27
	v_cvt_pk_bf16_f32 v21, v28, v29
	flat_store_dwordx4 v[36:37], v[18:21] offset:256
	s_nop 1
	v_add_u32_e32 v18, 0xb0, v142
	v_mad_i64_i32 v[20:21], s[28:29], v18, s95, v[144:145]
	v_lshl_add_u64 v[22:23], v[20:21], 0, v[140:141]
	v_lshl_add_u64 v[20:21], v[22:23], 0, s[46:47]
	v_add_co_u32_e32 v22, vcc, s16, v22
	v_ashrrev_i32_e32 v19, 31, v18
	s_nop 0
	v_addc_co_u32_e32 v23, vcc, 0, v23, vcc
	s_nop 1
	v_mov_b32_e32 v22, v242
	v_mov_b32_e32 v23, v243
	v_mov_b32_e32 v24, v244
	v_mov_b32_e32 v25, v245
	v_lshlrev_b64 v[18:19], 11, v[18:19]
	v_lshl_add_u64 v[18:19], s[26:27], 0, v[18:19]
	v_lshl_add_u64 v[18:19], v[18:19], 0, v[140:141]
	s_mov_b64 s[26:27], -1
	s_and_b64 vcc, exec, s[2:3]
	s_nop 0
	v_lshlrev_b32_e32 v26, 16, v22
	v_and_b32_e32 v27, 0xffff0000, v22
	v_lshlrev_b32_e32 v28, 16, v23
	v_and_b32_e32 v29, 0xffff0000, v23
	v_mul_f32_e32 v22, 0xbfb8aa3b, v26
	v_mul_f32_e32 v23, 0xbfb8aa3b, v27
	v_exp_f32_e32 v22, v22
	v_exp_f32_e32 v23, v23
	v_lshlrev_b32_e32 v30, 16, v24
	v_and_b32_e32 v24, 0xffff0000, v24
	v_add_f32_e32 v22, 1.0, v22
	v_add_f32_e32 v23, 1.0, v23
	v_rcp_f32_e32 v22, v22
	v_rcp_f32_e32 v23, v23
	v_lshlrev_b32_e32 v31, 16, v25
	v_and_b32_e32 v25, 0xffff0000, v25
	v_pk_mul_f32 v[14:15], v[14:15], v[22:23]
	v_mul_f32_e32 v22, 0xbfb8aa3b, v28
	v_mul_f32_e32 v23, 0xbfb8aa3b, v29
	v_exp_f32_e32 v22, v22
	v_exp_f32_e32 v23, v23
	v_add_f32_e32 v22, 1.0, v22
	v_add_f32_e32 v23, 1.0, v23
	v_rcp_f32_e32 v22, v22
	v_rcp_f32_e32 v23, v23
	s_nop 0
	v_pk_mul_f32 v[16:17], v[16:17], v[22:23]
	v_mul_f32_e32 v22, 0xbfb8aa3b, v30
	v_mul_f32_e32 v23, 0xbfb8aa3b, v24
	v_exp_f32_e32 v22, v22
	v_exp_f32_e32 v23, v23
	v_add_f32_e32 v22, 1.0, v22
	v_add_f32_e32 v23, 1.0, v23
	v_rcp_f32_e32 v22, v22
	v_rcp_f32_e32 v23, v23
	s_nop 0
	v_pk_mul_f32 v[22:23], v[10:11], v[22:23]
	v_mul_f32_e32 v10, 0xbfb8aa3b, v31
	v_mul_f32_e32 v11, 0xbfb8aa3b, v25
	v_exp_f32_e32 v10, v10
	v_exp_f32_e32 v11, v11
	v_add_f32_e32 v10, 1.0, v10
	v_add_f32_e32 v11, 1.0, v11
	v_rcp_f32_e32 v10, v10
	v_rcp_f32_e32 v11, v11
	s_nop 0
	v_pk_mul_f32 v[24:25], v[12:13], v[10:11]
	v_cvt_pk_bf16_f32 v10, v14, v15
	v_cvt_pk_bf16_f32 v11, v16, v17
	v_cvt_pk_bf16_f32 v12, v22, v23
	v_cvt_pk_bf16_f32 v13, v24, v25
	flat_store_dwordx4 v[18:19], v[10:13]
	s_nop 1
	v_mov_b32_e32 v10, v248
	v_mov_b32_e32 v11, v249
	v_mov_b32_e32 v12, v250
	v_mov_b32_e32 v13, v251
	s_nop 0
	v_lshlrev_b32_e32 v14, 16, v10
	v_and_b32_e32 v15, 0xffff0000, v10
	v_lshlrev_b32_e32 v16, 16, v11
	v_and_b32_e32 v17, 0xffff0000, v11
	v_mul_f32_e32 v10, 0xbfb8aa3b, v14
	v_mul_f32_e32 v11, 0xbfb8aa3b, v15
	v_exp_f32_e32 v10, v10
	v_exp_f32_e32 v11, v11
	v_lshlrev_b32_e32 v20, 16, v12
	v_and_b32_e32 v12, 0xffff0000, v12
	v_add_f32_e32 v10, 1.0, v10
	v_add_f32_e32 v11, 1.0, v11
	v_rcp_f32_e32 v10, v10
	v_rcp_f32_e32 v11, v11
	v_lshlrev_b32_e32 v21, 16, v13
	v_and_b32_e32 v13, 0xffff0000, v13
	v_pk_mul_f32 v[6:7], v[6:7], v[10:11]
	v_mul_f32_e32 v10, 0xbfb8aa3b, v16
	v_mul_f32_e32 v11, 0xbfb8aa3b, v17
	v_exp_f32_e32 v10, v10
	v_exp_f32_e32 v11, v11
	v_add_f32_e32 v10, 1.0, v10
	v_add_f32_e32 v11, 1.0, v11
	v_rcp_f32_e32 v10, v10
	v_rcp_f32_e32 v11, v11
	s_nop 0
	v_pk_mul_f32 v[8:9], v[8:9], v[10:11]
	v_mul_f32_e32 v10, 0xbfb8aa3b, v20
	v_mul_f32_e32 v11, 0xbfb8aa3b, v12
	v_exp_f32_e32 v10, v10
	v_exp_f32_e32 v11, v11
	v_add_f32_e32 v10, 1.0, v10
	v_add_f32_e32 v11, 1.0, v11
	v_rcp_f32_e32 v10, v10
	v_rcp_f32_e32 v11, v11
	s_nop 0
	v_pk_mul_f32 v[10:11], v[2:3], v[10:11]
	v_mul_f32_e32 v2, 0xbfb8aa3b, v21
	v_mul_f32_e32 v3, 0xbfb8aa3b, v13
	v_exp_f32_e32 v2, v2
	v_exp_f32_e32 v3, v3
	v_add_f32_e32 v2, 1.0, v2
	v_add_f32_e32 v3, 1.0, v3
	v_rcp_f32_e32 v2, v2
	v_rcp_f32_e32 v3, v3
	s_nop 0
	v_pk_mul_f32 v[12:13], v[4:5], v[2:3]
	v_cvt_pk_bf16_f32 v2, v6, v7
	v_cvt_pk_bf16_f32 v3, v8, v9
	v_cvt_pk_bf16_f32 v4, v10, v11
	v_cvt_pk_bf16_f32 v5, v12, v13
	flat_store_dwordx4 v[18:19], v[2:5] offset:256
	s_cbranch_vccnz .LBB0_1015
	s_andn2_b64 vcc, exec, s[18:19]
	s_cbranch_vccnz .LBB0_1014
	s_barrier
	s_branch .LBB0_1014

.LBB0_1048:
	v_mov_b32_e32 v140, v146
	s_mov_b32 s26, s84
	v_mov_b32_e32 v141, v147
	s_mov_b32 s27, s44
	v_mov_b32_e32 v142, s50
	ds_read_b64 v[142:143], v142
	s_lshl_b32 s16, s16, 8
	s_lshl_b32 s26, s26, 5
	s_add_i32 s26, s26, s16
	s_lshl_b32 s37, s37, 8
	s_lshl_b32 s46, s27, 6
	v_lshl_add_u32 v140, v140, 3, s26
	s_waitcnt lgkmcnt(0)
	v_readfirstlane_b32 s26, v142
	v_readfirstlane_b32 s16, v143
	s_add_u32 s28, s26, 0x8bf0000
	s_addc_u32 s29, s16, 0
	s_add_u32 s26, s26, 0x4bf0000
	s_addc_u32 s27, s16, 0
	s_add_i32 s46, s46, s37
	v_add_u32_e32 v144, s46, v141
	v_mov_b64_e32 v[142:143], s[28:29]
	v_ashrrev_i32_e32 v141, 31, v140
	v_mad_i64_i32 v[150:151], s[28:29], v144, s95, v[142:143]
	v_lshlrev_b64 v[140:141], 1, v[140:141]
	v_lshl_add_u64 v[150:151], v[150:151], 0, v[140:141]
	s_mov_b64 s[46:47], 0x2680
	s_movk_i32 s16, 0x2000
	v_ashrrev_i32_e32 v145, 31, v144
	v_lshl_add_u64 v[156:157], v[150:151], 0, s[46:47]
	v_add_co_u32_e32 v150, vcc, s16, v150
	v_lshlrev_b64 v[152:153], 11, v[144:145]
	s_nop 0
	v_addc_co_u32_e32 v151, vcc, 0, v151, vcc
	v_lshl_add_u64 v[154:155], s[26:27], 0, v[152:153]
	flat_load_dwordx4 v[150:153], v[150:151] offset:1664
	v_lshl_add_u64 v[246:247], v[142:143], 0, v[140:141]
	v_lshl_add_u64 v[246:247], v[246:247], 0, s[46:47]
	v_lshl_add_u64 v[198:199], v[140:141], 0, s[26:27]
	v_lshlrev_b32_e32 v170, 11, v144
	v_mad_u64_u32 v[168:169], s[100:101], v170, 1, v[198:199]
	global_load_dwordx4 v[168:171], v[168:169], off
	v_mad_i64_i32 v[172:173], s[100:101], v144, s95, v[246:247]
	global_load_dwordx4 v[172:175], v[172:173], off offset:256
	v_lshlrev_b32_e32 v178, 11, v144
	v_mad_u64_u32 v[176:177], s[100:101], v178, 1, v[198:199]
	global_load_dwordx4 v[176:179], v[176:177], off offset:256
	v_add_u32_e32 v184, 16, v144
	v_mad_i64_i32 v[182:183], s[100:101], v184, s95, v[246:247]
	global_load_dwordx4 v[182:185], v[182:183], off
	v_add_u32_e32 v188, 16, v144
	v_lshlrev_b32_e32 v188, 11, v188
	v_mad_u64_u32 v[186:187], s[100:101], v188, 1, v[198:199]
	global_load_dwordx4 v[186:189], v[186:187], off
	v_add_u32_e32 v192, 16, v144
	v_mad_i64_i32 v[190:191], s[100:101], v192, s95, v[246:247]
	global_load_dwordx4 v[190:193], v[190:191], off offset:256
	v_add_u32_e32 v196, 16, v144
	v_lshlrev_b32_e32 v196, 11, v196
	v_mad_u64_u32 v[194:195], s[100:101], v196, 1, v[198:199]
	global_load_dwordx4 v[194:197], v[194:195], off offset:256
	v_add_u32_e32 v220, 32, v144
	v_mad_i64_i32 v[218:219], s[100:101], v220, s95, v[246:247]
	global_load_dwordx4 v[218:221], v[218:219], off
	v_add_u32_e32 v224, 32, v144
	v_lshlrev_b32_e32 v224, 11, v224
	v_mad_u64_u32 v[222:223], s[100:101], v224, 1, v[198:199]
	global_load_dwordx4 v[222:225], v[222:223], off
	v_add_u32_e32 v232, 32, v144
	v_mad_i64_i32 v[230:231], s[100:101], v232, s95, v[246:247]
	global_load_dwordx4 v[230:233], v[230:231], off offset:256
	v_add_u32_e32 v236, 32, v144
	v_lshlrev_b32_e32 v236, 11, v236
	v_mad_u64_u32 v[234:235], s[100:101], v236, 1, v[198:199]
	global_load_dwordx4 v[234:237], v[234:235], off offset:256
	v_add_u32_e32 v240, 48, v144
	v_mad_i64_i32 v[238:239], s[100:101], v240, s95, v[246:247]
	global_load_dwordx4 v[238:241], v[238:239], off
	v_add_u32_e32 v244, 48, v144
	v_lshlrev_b32_e32 v244, 11, v244
	v_mad_u64_u32 v[242:243], s[100:101], v244, 1, v[198:199]
	global_load_dwordx4 v[242:245], v[242:243], off
	v_lshl_add_u64 v[154:155], v[154:155], 0, v[140:141]
	s_waitcnt vmcnt(0) lgkmcnt(0)
	v_lshlrev_b32_e32 v145, 16, v150
	v_mul_f32_e32 v145, 0xbfb8aa3b, v145
	v_exp_f32_e32 v145, v145
	v_and_b32_e32 v150, 0xffff0000, v150
	v_lshlrev_b32_e32 v160, 16, v151
	v_and_b32_e32 v151, 0xffff0000, v151
	v_add_f32_e32 v145, 1.0, v145
	v_rcp_f32_e32 v158, v145
	v_mul_f32_e32 v145, 0xbfb8aa3b, v150
	v_exp_f32_e32 v145, v145
	v_lshlrev_b32_e32 v162, 16, v152
	v_and_b32_e32 v152, 0xffff0000, v152
	v_lshlrev_b32_e32 v164, 16, v153
	v_add_f32_e32 v145, 1.0, v145
	v_rcp_f32_e32 v159, v145
	v_mul_f32_e32 v145, 0xbfb8aa3b, v160
	v_exp_f32_e32 v145, v145
	v_and_b32_e32 v153, 0xffff0000, v153
	v_add_f32_e32 v145, 1.0, v145
	v_rcp_f32_e32 v160, v145
	v_mul_f32_e32 v145, 0xbfb8aa3b, v151
	v_exp_f32_e32 v145, v145
	s_nop 0
	v_add_f32_e32 v145, 1.0, v145
	v_rcp_f32_e32 v161, v145
	v_mul_f32_e32 v145, 0xbfb8aa3b, v162
	v_exp_f32_e32 v145, v145
	s_nop 0
	v_add_f32_e32 v145, 1.0, v145
	v_rcp_f32_e32 v162, v145
	v_mul_f32_e32 v145, 0xbfb8aa3b, v152
	v_exp_f32_e32 v145, v145
	s_nop 0
	v_add_f32_e32 v145, 1.0, v145
	v_rcp_f32_e32 v163, v145
	v_mul_f32_e32 v145, 0xbfb8aa3b, v164
	v_exp_f32_e32 v145, v145
	s_nop 0
	v_add_f32_e32 v145, 1.0, v145
	v_rcp_f32_e32 v164, v145
	v_mul_f32_e32 v145, 0xbfb8aa3b, v153
	s_nop 1
	v_mov_b32_e32 v150, v168
	v_mov_b32_e32 v151, v169
	v_mov_b32_e32 v152, v170
	v_mov_b32_e32 v153, v171
	v_exp_f32_e32 v145, v145
	s_nop 0
	v_lshlrev_b32_e32 v166, 16, v150
	v_add_f32_e32 v145, 1.0, v145
	v_rcp_f32_e32 v165, v145
	v_and_b32_e32 v167, 0xffff0000, v150
	v_lshlrev_b32_e32 v150, 16, v151
	v_and_b32_e32 v151, 0xffff0000, v151
	v_pk_fma_f32 v[128:129], v[128:129], v[160:161], v[150:151]
	v_lshlrev_b32_e32 v150, 16, v152
	v_and_b32_e32 v151, 0xffff0000, v152
	v_pk_fma_f32 v[150:151], v[122:123], v[162:163], v[150:151]
	v_lshlrev_b32_e32 v122, 16, v153
	v_and_b32_e32 v123, 0xffff0000, v153
	v_pk_fma_f32 v[126:127], v[126:127], v[158:159], v[166:167]
	v_pk_fma_f32 v[152:153], v[124:125], v[164:165], v[122:123]
	v_cvt_pk_bf16_f32 v122, v126, v127
	v_cvt_pk_bf16_f32 v123, v128, v129
	v_cvt_pk_bf16_f32 v124, v150, v151
	v_cvt_pk_bf16_f32 v125, v152, v153
	flat_store_dwordx4 v[154:155], v[122:125]
	s_nop 1
	v_mov_b32_e32 v122, v172
	v_mov_b32_e32 v123, v173
	v_mov_b32_e32 v124, v174
	v_mov_b32_e32 v125, v175
	s_nop 0
	v_lshlrev_b32_e32 v126, 16, v122
	v_and_b32_e32 v122, 0xffff0000, v122
	v_mul_f32_e32 v122, 0xbfb8aa3b, v122
	v_exp_f32_e32 v122, v122
	v_lshlrev_b32_e32 v128, 16, v123
	v_and_b32_e32 v123, 0xffff0000, v123
	v_lshlrev_b32_e32 v145, 16, v124
	v_add_f32_e32 v122, 1.0, v122
	v_rcp_f32_e32 v127, v122
	v_mul_f32_e32 v122, 0xbfb8aa3b, v128
	v_exp_f32_e32 v122, v122
	v_and_b32_e32 v124, 0xffff0000, v124
	v_lshlrev_b32_e32 v152, 16, v125
	v_and_b32_e32 v125, 0xffff0000, v125
	v_add_f32_e32 v122, 1.0, v122
	v_rcp_f32_e32 v128, v122
	v_mul_f32_e32 v122, 0xbfb8aa3b, v123
	v_exp_f32_e32 v122, v122
	v_mul_f32_e32 v126, 0xbfb8aa3b, v126
	v_exp_f32_e32 v126, v126
	v_add_f32_e32 v122, 1.0, v122
	v_rcp_f32_e32 v129, v122
	v_mul_f32_e32 v122, 0xbfb8aa3b, v145
	v_exp_f32_e32 v122, v122
	v_add_f32_e32 v126, 1.0, v126
	v_rcp_f32_e32 v126, v126
	v_add_f32_e32 v122, 1.0, v122
	v_rcp_f32_e32 v150, v122
	v_mul_f32_e32 v122, 0xbfb8aa3b, v124
	v_exp_f32_e32 v122, v122
	s_nop 0
	v_add_f32_e32 v122, 1.0, v122
	v_rcp_f32_e32 v151, v122
	v_mul_f32_e32 v122, 0xbfb8aa3b, v152
	v_exp_f32_e32 v122, v122
	s_nop 0
	v_add_f32_e32 v122, 1.0, v122
	v_rcp_f32_e32 v152, v122
	v_mul_f32_e32 v122, 0xbfb8aa3b, v125
	v_exp_f32_e32 v122, v122
	s_nop 0
	v_add_f32_e32 v122, 1.0, v122
	v_rcp_f32_e32 v153, v122
	s_nop 1
	v_mov_b32_e32 v122, v176
	v_mov_b32_e32 v123, v177
	v_mov_b32_e32 v124, v178
	v_mov_b32_e32 v125, v179
	s_nop 0
	v_lshlrev_b32_e32 v156, 16, v122
	v_and_b32_e32 v157, 0xffff0000, v122
	v_lshlrev_b32_e32 v122, 16, v123
	v_and_b32_e32 v123, 0xffff0000, v123
	v_pk_fma_f32 v[120:121], v[120:121], v[128:129], v[122:123]
	v_lshlrev_b32_e32 v122, 16, v124
	v_and_b32_e32 v123, 0xffff0000, v124
	v_pk_fma_f32 v[122:123], v[114:115], v[150:151], v[122:123]
	v_lshlrev_b32_e32 v114, 16, v125
	v_and_b32_e32 v115, 0xffff0000, v125
	v_pk_fma_f32 v[118:119], v[118:119], v[126:127], v[156:157]
	v_pk_fma_f32 v[124:125], v[116:117], v[152:153], v[114:115]
	v_cvt_pk_bf16_f32 v114, v118, v119
	v_cvt_pk_bf16_f32 v115, v120, v121
	v_cvt_pk_bf16_f32 v116, v122, v123
	v_cvt_pk_bf16_f32 v117, v124, v125
	flat_store_dwordx4 v[154:155], v[114:117] offset:256
	s_nop 1
	v_add_u32_e32 v114, 16, v144
	v_mad_i64_i32 v[116:117], s[28:29], v114, s95, v[142:143]
	v_lshl_add_u64 v[118:119], v[116:117], 0, v[140:141]
	v_lshl_add_u64 v[116:117], v[118:119], 0, s[46:47]
	v_add_co_u32_e32 v118, vcc, s16, v118
	v_ashrrev_i32_e32 v115, 31, v114
	s_nop 0
	v_addc_co_u32_e32 v119, vcc, 0, v119, vcc
	s_nop 1
	v_mov_b32_e32 v118, v182
	v_mov_b32_e32 v119, v183
	v_mov_b32_e32 v120, v184
	v_mov_b32_e32 v121, v185
	v_lshlrev_b64 v[114:115], 11, v[114:115]
	v_lshl_add_u64 v[114:115], s[26:27], 0, v[114:115]
	v_lshl_add_u64 v[114:115], v[114:115], 0, v[140:141]
	s_nop 0
	v_lshlrev_b32_e32 v122, 16, v118
	v_and_b32_e32 v118, 0xffff0000, v118
	v_mul_f32_e32 v118, 0xbfb8aa3b, v118
	v_exp_f32_e32 v118, v118
	v_lshlrev_b32_e32 v123, 16, v119
	v_and_b32_e32 v119, 0xffff0000, v119
	v_lshlrev_b32_e32 v128, 16, v120
	v_add_f32_e32 v118, 1.0, v118
	v_rcp_f32_e32 v125, v118
	v_mul_f32_e32 v118, 0xbfb8aa3b, v123
	v_exp_f32_e32 v118, v118
	v_mul_f32_e32 v122, 0xbfb8aa3b, v122
	v_exp_f32_e32 v122, v122
	v_and_b32_e32 v120, 0xffff0000, v120
	v_add_f32_e32 v118, 1.0, v118
	v_rcp_f32_e32 v126, v118
	v_mul_f32_e32 v118, 0xbfb8aa3b, v119
	v_exp_f32_e32 v118, v118
	v_lshlrev_b32_e32 v145, 16, v121
	v_and_b32_e32 v121, 0xffff0000, v121
	v_add_f32_e32 v122, 1.0, v122
	v_add_f32_e32 v118, 1.0, v118
	v_rcp_f32_e32 v127, v118
	v_mul_f32_e32 v118, 0xbfb8aa3b, v128
	v_exp_f32_e32 v118, v118
	v_rcp_f32_e32 v124, v122
	v_mul_f32_e32 v119, 0xbfb8aa3b, v121
	v_exp_f32_e32 v119, v119
	v_add_f32_e32 v118, 1.0, v118
	v_rcp_f32_e32 v128, v118
	v_mul_f32_e32 v118, 0xbfb8aa3b, v120
	s_nop 1
	v_mov_b32_e32 v120, v186
	v_mov_b32_e32 v121, v187
	v_mov_b32_e32 v122, v188
	v_mov_b32_e32 v123, v189
	v_exp_f32_e32 v118, v118
	v_add_f32_e32 v119, 1.0, v119
	v_rcp_f32_e32 v119, v119
	v_add_f32_e32 v118, 1.0, v118
	v_rcp_f32_e32 v129, v118
	v_mul_f32_e32 v118, 0xbfb8aa3b, v145
	v_exp_f32_e32 v118, v118
	s_nop 0
	v_lshlrev_b32_e32 v150, 16, v120
	v_add_f32_e32 v118, 1.0, v118
	v_rcp_f32_e32 v118, v118
	v_and_b32_e32 v151, 0xffff0000, v120
	v_lshlrev_b32_e32 v120, 16, v121
	v_and_b32_e32 v121, 0xffff0000, v121
	v_pk_fma_f32 v[112:113], v[112:113], v[126:127], v[120:121]
	v_lshlrev_b32_e32 v120, 16, v122
	v_and_b32_e32 v121, 0xffff0000, v122
	v_pk_fma_f32 v[120:121], v[106:107], v[128:129], v[120:121]
	v_lshlrev_b32_e32 v106, 16, v123
	v_and_b32_e32 v107, 0xffff0000, v123
	v_pk_fma_f32 v[110:111], v[110:111], v[124:125], v[150:151]
	v_pk_fma_f32 v[118:119], v[108:109], v[118:119], v[106:107]
	v_cvt_pk_bf16_f32 v106, v110, v111
	v_cvt_pk_bf16_f32 v107, v112, v113
	v_cvt_pk_bf16_f32 v108, v120, v121
	v_cvt_pk_bf16_f32 v109, v118, v119
	flat_store_dwordx4 v[114:115], v[106:109]
	s_nop 1
	v_mov_b32_e32 v106, v190
	v_mov_b32_e32 v107, v191
	v_mov_b32_e32 v108, v192
	v_mov_b32_e32 v109, v193
	s_nop 0
	v_lshlrev_b32_e32 v110, 16, v106
	v_and_b32_e32 v111, 0xffff0000, v106
	v_lshlrev_b32_e32 v112, 16, v107
	v_and_b32_e32 v113, 0xffff0000, v107
	v_lshlrev_b32_e32 v116, 16, v108
	v_and_b32_e32 v117, 0xffff0000, v108
	v_lshlrev_b32_e32 v118, 16, v109
	v_and_b32_e32 v119, 0xffff0000, v109
	v_mul_f32_e32 v106, 0xbfb8aa3b, v110
	v_mul_f32_e32 v107, 0xbfb8aa3b, v111
	v_mul_f32_e32 v108, 0xbfb8aa3b, v112
	v_mul_f32_e32 v109, 0xbfb8aa3b, v113
	v_mul_f32_e32 v110, 0xbfb8aa3b, v116
	v_mul_f32_e32 v111, 0xbfb8aa3b, v117
	v_mul_f32_e32 v112, 0xbfb8aa3b, v118
	v_mul_f32_e32 v113, 0xbfb8aa3b, v119
	s_nop 1
	v_mov_b32_e32 v116, v194
	v_mov_b32_e32 v117, v195
	v_mov_b32_e32 v118, v196
	v_mov_b32_e32 v119, v197
	v_exp_f32_e32 v106, v106
	v_exp_f32_e32 v107, v107
	v_exp_f32_e32 v108, v108
	v_exp_f32_e32 v109, v109
	v_exp_f32_e32 v110, v110
	v_exp_f32_e32 v111, v111
	v_exp_f32_e32 v112, v112
	v_exp_f32_e32 v113, v113
	v_add_f32_e32 v106, 1.0, v106
	v_add_f32_e32 v107, 1.0, v107
	v_rcp_f32_e32 v106, v106
	v_rcp_f32_e32 v107, v107
	v_add_f32_e32 v108, 1.0, v108
	v_add_f32_e32 v109, 1.0, v109
	v_rcp_f32_e32 v108, v108
	v_rcp_f32_e32 v109, v109
	v_add_f32_e32 v110, 1.0, v110
	v_add_f32_e32 v111, 1.0, v111
	v_rcp_f32_e32 v110, v110
	v_rcp_f32_e32 v111, v111
	v_add_f32_e32 v112, 1.0, v112
	v_add_f32_e32 v113, 1.0, v113
	v_rcp_f32_e32 v112, v112
	v_rcp_f32_e32 v113, v113
	s_nop 0
	v_lshlrev_b32_e32 v120, 16, v116
	v_and_b32_e32 v121, 0xffff0000, v116
	v_pk_fma_f32 v[102:103], v[102:103], v[106:107], v[120:121]
	v_lshlrev_b32_e32 v106, 16, v117
	v_and_b32_e32 v107, 0xffff0000, v117
	v_pk_fma_f32 v[104:105], v[104:105], v[108:109], v[106:107]
	v_lshlrev_b32_e32 v106, 16, v118
	v_and_b32_e32 v107, 0xffff0000, v118
	v_pk_fma_f32 v[106:107], v[98:99], v[110:111], v[106:107]
	v_lshlrev_b32_e32 v98, 16, v119
	v_and_b32_e32 v99, 0xffff0000, v119
	v_pk_fma_f32 v[108:109], v[100:101], v[112:113], v[98:99]
	v_cvt_pk_bf16_f32 v98, v102, v103
	v_cvt_pk_bf16_f32 v99, v104, v105
	v_cvt_pk_bf16_f32 v100, v106, v107
	v_cvt_pk_bf16_f32 v101, v108, v109
	flat_store_dwordx4 v[114:115], v[98:101] offset:256
	s_nop 1
	v_add_u32_e32 v98, 32, v144
	v_ashrrev_i32_e32 v99, 31, v98
	v_mad_i64_i32 v[102:103], s[28:29], v98, s95, v[142:143]
	v_lshlrev_b64 v[98:99], 11, v[98:99]
	v_lshl_add_u64 v[102:103], v[102:103], 0, v[140:141]
	v_lshl_add_u64 v[100:101], s[26:27], 0, v[98:99]
	v_lshl_add_u64 v[98:99], v[102:103], 0, s[46:47]
	v_add_co_u32_e32 v102, vcc, s16, v102
	v_lshl_add_u64 v[100:101], v[100:101], 0, v[140:141]
	s_nop 0
	v_addc_co_u32_e32 v103, vcc, 0, v103, vcc
	s_nop 1
	v_mov_b32_e32 v102, v218
	v_mov_b32_e32 v103, v219
	v_mov_b32_e32 v104, v220
	v_mov_b32_e32 v105, v221
	s_nop 0
	v_lshlrev_b32_e32 v106, 16, v102
	v_and_b32_e32 v102, 0xffff0000, v102
	v_mul_f32_e32 v102, 0xbfb8aa3b, v102
	v_exp_f32_e32 v102, v102
	v_lshlrev_b32_e32 v107, 16, v103
	v_lshlrev_b32_e32 v110, 16, v105
	v_and_b32_e32 v111, 0xffff0000, v105
	v_add_f32_e32 v102, 1.0, v102
	v_rcp_f32_e32 v105, v102
	v_mul_f32_e32 v102, 0xbfb8aa3b, v107
	v_exp_f32_e32 v102, v102
	v_and_b32_e32 v103, 0xffff0000, v103
	v_lshlrev_b32_e32 v108, 16, v104
	v_and_b32_e32 v109, 0xffff0000, v104
	v_add_f32_e32 v102, 1.0, v102
	v_mul_f32_e32 v104, 0xbfb8aa3b, v106
	v_rcp_f32_e32 v106, v102
	v_mul_f32_e32 v102, 0xbfb8aa3b, v103
	v_exp_f32_e32 v102, v102
	v_mul_f32_e32 v103, 0xbfb8aa3b, v111
	v_exp_f32_e32 v104, v104
	v_exp_f32_e32 v103, v103
	v_add_f32_e32 v102, 1.0, v102
	v_rcp_f32_e32 v107, v102
	v_mul_f32_e32 v102, 0xbfb8aa3b, v108
	v_exp_f32_e32 v102, v102
	v_add_f32_e32 v104, 1.0, v104
	v_rcp_f32_e32 v104, v104
	v_add_f32_e32 v103, 1.0, v103
	v_add_f32_e32 v102, 1.0, v102
	v_rcp_f32_e32 v108, v102
	v_mul_f32_e32 v102, 0xbfb8aa3b, v109
	v_exp_f32_e32 v102, v102
	v_rcp_f32_e32 v103, v103
	v_add_f32_e32 v102, 1.0, v102
	v_rcp_f32_e32 v109, v102
	v_mul_f32_e32 v102, 0xbfb8aa3b, v110
	s_nop 1
	v_mov_b32_e32 v110, v222
	v_mov_b32_e32 v111, v223
	v_mov_b32_e32 v112, v224
	v_mov_b32_e32 v113, v225
	v_exp_f32_e32 v102, v102
	s_nop 0
	v_lshlrev_b32_e32 v114, 16, v110
	v_add_f32_e32 v102, 1.0, v102
	v_rcp_f32_e32 v102, v102
	v_and_b32_e32 v115, 0xffff0000, v110
	v_pk_fma_f32 v[94:95], v[94:95], v[104:105], v[114:115]
	v_lshlrev_b32_e32 v104, 16, v111
	v_and_b32_e32 v105, 0xffff0000, v111
	v_pk_fma_f32 v[96:97], v[96:97], v[106:107], v[104:105]
	v_lshlrev_b32_e32 v104, 16, v112
	v_and_b32_e32 v105, 0xffff0000, v112
	v_pk_fma_f32 v[104:105], v[90:91], v[108:109], v[104:105]
	v_lshlrev_b32_e32 v90, 16, v113
	v_and_b32_e32 v91, 0xffff0000, v113
	v_pk_fma_f32 v[102:103], v[92:93], v[102:103], v[90:91]
	v_cvt_pk_bf16_f32 v90, v94, v95
	v_cvt_pk_bf16_f32 v91, v96, v97
	v_cvt_pk_bf16_f32 v92, v104, v105
	v_cvt_pk_bf16_f32 v93, v102, v103
	flat_store_dwordx4 v[100:101], v[90:93]
	s_nop 1
	v_mov_b32_e32 v90, v230
	v_mov_b32_e32 v91, v231
	v_mov_b32_e32 v92, v232
	v_mov_b32_e32 v93, v233
	s_nop 0
	v_lshlrev_b32_e32 v96, 16, v91
	v_and_b32_e32 v97, 0xffff0000, v91
	v_lshlrev_b32_e32 v102, 16, v93
	v_and_b32_e32 v103, 0xffff0000, v93
	v_lshlrev_b32_e32 v98, 16, v92
	v_and_b32_e32 v99, 0xffff0000, v92
	v_mul_f32_e32 v92, 0xbfb8aa3b, v96
	v_mul_f32_e32 v93, 0xbfb8aa3b, v97
	v_mul_f32_e32 v96, 0xbfb8aa3b, v102
	v_mul_f32_e32 v97, 0xbfb8aa3b, v103
	s_nop 1
	v_mov_b32_e32 v102, v234
	v_mov_b32_e32 v103, v235
	v_mov_b32_e32 v104, v236
	v_mov_b32_e32 v105, v237
	v_lshlrev_b32_e32 v94, 16, v90
	v_and_b32_e32 v95, 0xffff0000, v90
	v_mul_f32_e32 v90, 0xbfb8aa3b, v94
	v_mul_f32_e32 v91, 0xbfb8aa3b, v95
	v_exp_f32_e32 v90, v90
	v_exp_f32_e32 v91, v91
	v_exp_f32_e32 v92, v92
	v_exp_f32_e32 v93, v93
	v_mul_f32_e32 v94, 0xbfb8aa3b, v98
	v_mul_f32_e32 v95, 0xbfb8aa3b, v99
	v_exp_f32_e32 v94, v94
	v_exp_f32_e32 v95, v95
	v_exp_f32_e32 v96, v96
	v_exp_f32_e32 v97, v97
	v_add_f32_e32 v90, 1.0, v90
	v_add_f32_e32 v91, 1.0, v91
	v_rcp_f32_e32 v90, v90
	v_rcp_f32_e32 v91, v91
	v_add_f32_e32 v92, 1.0, v92
	v_add_f32_e32 v93, 1.0, v93
	v_rcp_f32_e32 v92, v92
	v_rcp_f32_e32 v93, v93
	v_add_f32_e32 v94, 1.0, v94
	v_add_f32_e32 v95, 1.0, v95
	v_rcp_f32_e32 v94, v94
	v_rcp_f32_e32 v95, v95
	v_add_f32_e32 v96, 1.0, v96
	v_add_f32_e32 v97, 1.0, v97
	v_rcp_f32_e32 v96, v96
	v_rcp_f32_e32 v97, v97
	s_nop 0
	v_lshlrev_b32_e32 v98, 16, v102
	v_and_b32_e32 v99, 0xffff0000, v102
	v_pk_fma_f32 v[86:87], v[86:87], v[90:91], v[98:99]
	v_lshlrev_b32_e32 v90, 16, v103
	v_and_b32_e32 v91, 0xffff0000, v103
	v_pk_fma_f32 v[88:89], v[88:89], v[92:93], v[90:91]
	v_lshlrev_b32_e32 v90, 16, v104
	v_and_b32_e32 v91, 0xffff0000, v104
	v_pk_fma_f32 v[90:91], v[82:83], v[94:95], v[90:91]
	v_lshlrev_b32_e32 v82, 16, v105
	v_and_b32_e32 v83, 0xffff0000, v105
	v_pk_fma_f32 v[92:93], v[84:85], v[96:97], v[82:83]
	v_cvt_pk_bf16_f32 v82, v86, v87
	v_cvt_pk_bf16_f32 v83, v88, v89
	v_cvt_pk_bf16_f32 v84, v90, v91
	v_cvt_pk_bf16_f32 v85, v92, v93
	flat_store_dwordx4 v[100:101], v[82:85] offset:256
	s_nop 1
	v_add_u32_e32 v82, 48, v144
	v_ashrrev_i32_e32 v83, 31, v82
	v_mad_i64_i32 v[86:87], s[28:29], v82, s95, v[142:143]
	v_lshlrev_b64 v[82:83], 11, v[82:83]
	v_lshl_add_u64 v[86:87], v[86:87], 0, v[140:141]
	v_lshl_add_u64 v[84:85], s[26:27], 0, v[82:83]
	v_lshl_add_u64 v[82:83], v[86:87], 0, s[46:47]
	v_add_co_u32_e32 v86, vcc, s16, v86
	v_lshl_add_u64 v[84:85], v[84:85], 0, v[140:141]
	s_nop 0
	v_addc_co_u32_e32 v87, vcc, 0, v87, vcc
	s_nop 1
	v_mov_b32_e32 v86, v238
	v_mov_b32_e32 v87, v239
	v_mov_b32_e32 v88, v240
	v_mov_b32_e32 v89, v241
	s_nop 0
	v_lshlrev_b32_e32 v90, 16, v86
	v_and_b32_e32 v86, 0xffff0000, v86
	v_mul_f32_e32 v86, 0xbfb8aa3b, v86
	v_exp_f32_e32 v86, v86
	v_lshlrev_b32_e32 v91, 16, v87
	v_lshlrev_b32_e32 v94, 16, v89
	v_and_b32_e32 v95, 0xffff0000, v89
	v_add_f32_e32 v86, 1.0, v86
	v_rcp_f32_e32 v89, v86
	v_mul_f32_e32 v86, 0xbfb8aa3b, v91
	v_exp_f32_e32 v86, v86
	v_and_b32_e32 v87, 0xffff0000, v87
	v_lshlrev_b32_e32 v92, 16, v88
	v_and_b32_e32 v93, 0xffff0000, v88
	v_add_f32_e32 v86, 1.0, v86
	v_mul_f32_e32 v88, 0xbfb8aa3b, v90
	v_rcp_f32_e32 v90, v86
	v_mul_f32_e32 v86, 0xbfb8aa3b, v87
	v_exp_f32_e32 v86, v86
	v_mul_f32_e32 v87, 0xbfb8aa3b, v95
	v_exp_f32_e32 v88, v88
	v_exp_f32_e32 v87, v87
	v_add_f32_e32 v86, 1.0, v86
	v_rcp_f32_e32 v91, v86
	v_mul_f32_e32 v86, 0xbfb8aa3b, v92
	v_exp_f32_e32 v86, v86
	v_add_f32_e32 v88, 1.0, v88
	v_rcp_f32_e32 v88, v88
	v_add_f32_e32 v87, 1.0, v87
	v_add_f32_e32 v86, 1.0, v86
	v_rcp_f32_e32 v92, v86
	v_mul_f32_e32 v86, 0xbfb8aa3b, v93
	v_exp_f32_e32 v86, v86
	v_rcp_f32_e32 v87, v87
	v_add_f32_e32 v86, 1.0, v86
	v_rcp_f32_e32 v93, v86
	v_mul_f32_e32 v86, 0xbfb8aa3b, v94
	s_nop 1
	v_mov_b32_e32 v94, v242
	v_mov_b32_e32 v95, v243
	v_mov_b32_e32 v96, v244
	v_mov_b32_e32 v97, v245
	v_add_u32_e32 v170, 48, v144
	v_mad_i64_i32 v[168:169], s[100:101], v170, s95, v[246:247]
	global_load_dwordx4 v[168:171], v[168:169], off offset:256
	v_add_u32_e32 v174, 48, v144
	v_lshlrev_b32_e32 v174, 11, v174
	v_mad_u64_u32 v[172:173], s[100:101], v174, 1, v[198:199]
	global_load_dwordx4 v[172:175], v[172:173], off offset:256
	v_add_u32_e32 v178, 128, v144
	v_mad_i64_i32 v[176:177], s[100:101], v178, s95, v[246:247]
	global_load_dwordx4 v[176:179], v[176:177], off
	v_add_u32_e32 v184, 128, v144
	v_lshlrev_b32_e32 v184, 11, v184
	v_mad_u64_u32 v[182:183], s[100:101], v184, 1, v[198:199]
	global_load_dwordx4 v[182:185], v[182:183], off
	v_add_u32_e32 v188, 128, v144
	v_mad_i64_i32 v[186:187], s[100:101], v188, s95, v[246:247]
	global_load_dwordx4 v[186:189], v[186:187], off offset:256
	v_add_u32_e32 v192, 128, v144
	v_lshlrev_b32_e32 v192, 11, v192
	v_mad_u64_u32 v[190:191], s[100:101], v192, 1, v[198:199]
	global_load_dwordx4 v[190:193], v[190:191], off offset:256
	v_add_u32_e32 v196, 144, v144
	v_mad_i64_i32 v[194:195], s[100:101], v196, s95, v[246:247]
	global_load_dwordx4 v[194:197], v[194:195], off
	v_add_u32_e32 v220, 144, v144
	v_lshlrev_b32_e32 v220, 11, v220
	v_mad_u64_u32 v[218:219], s[100:101], v220, 1, v[198:199]
	global_load_dwordx4 v[218:221], v[218:219], off
	v_add_u32_e32 v224, 144, v144
	v_mad_i64_i32 v[222:223], s[100:101], v224, s95, v[246:247]
	global_load_dwordx4 v[222:225], v[222:223], off offset:256
	v_add_u32_e32 v232, 144, v144
	v_lshlrev_b32_e32 v232, 11, v232
	v_mad_u64_u32 v[230:231], s[100:101], v232, 1, v[198:199]
	global_load_dwordx4 v[230:233], v[230:231], off offset:256
	v_add_u32_e32 v236, 160, v144
	v_mad_i64_i32 v[234:235], s[100:101], v236, s95, v[246:247]
	global_load_dwordx4 v[234:237], v[234:235], off
	v_add_u32_e32 v240, 160, v144
	v_lshlrev_b32_e32 v240, 11, v240
	v_mad_u64_u32 v[238:239], s[100:101], v240, 1, v[198:199]
	global_load_dwordx4 v[238:241], v[238:239], off
	v_add_u32_e32 v244, 160, v144
	v_mad_i64_i32 v[242:243], s[100:101], v244, s95, v[246:247]
	global_load_dwordx4 v[242:245], v[242:243], off offset:256
	v_add_u32_e32 v250, 160, v144
	v_lshlrev_b32_e32 v250, 11, v250
	v_mad_u64_u32 v[248:249], s[100:101], v250, 1, v[198:199]
	global_load_dwordx4 v[248:251], v[248:249], off offset:256
	v_exp_f32_e32 v86, v86
	s_nop 0
	v_lshlrev_b32_e32 v98, 16, v94
	v_add_f32_e32 v86, 1.0, v86
	v_rcp_f32_e32 v86, v86
	v_and_b32_e32 v99, 0xffff0000, v94
	v_pk_fma_f32 v[78:79], v[78:79], v[88:89], v[98:99]
	v_lshlrev_b32_e32 v88, 16, v95
	v_and_b32_e32 v89, 0xffff0000, v95
	v_pk_fma_f32 v[80:81], v[80:81], v[90:91], v[88:89]
	v_lshlrev_b32_e32 v88, 16, v96
	v_and_b32_e32 v89, 0xffff0000, v96
	v_pk_fma_f32 v[88:89], v[74:75], v[92:93], v[88:89]
	v_lshlrev_b32_e32 v74, 16, v97
	v_and_b32_e32 v75, 0xffff0000, v97
	v_pk_fma_f32 v[86:87], v[76:77], v[86:87], v[74:75]
	v_cvt_pk_bf16_f32 v74, v78, v79
	v_cvt_pk_bf16_f32 v75, v80, v81
	v_cvt_pk_bf16_f32 v76, v88, v89
	v_cvt_pk_bf16_f32 v77, v86, v87
	flat_store_dwordx4 v[84:85], v[74:77]
	s_waitcnt vmcnt(0)
	s_nop 1
	v_mov_b32_e32 v74, v168
	v_mov_b32_e32 v75, v169
	v_mov_b32_e32 v76, v170
	v_mov_b32_e32 v77, v171
	s_nop 0
	v_lshlrev_b32_e32 v80, 16, v75
	v_and_b32_e32 v81, 0xffff0000, v75
	v_lshlrev_b32_e32 v86, 16, v77
	v_and_b32_e32 v87, 0xffff0000, v77
	v_lshlrev_b32_e32 v82, 16, v76
	v_and_b32_e32 v83, 0xffff0000, v76
	v_mul_f32_e32 v76, 0xbfb8aa3b, v80
	v_mul_f32_e32 v77, 0xbfb8aa3b, v81
	v_mul_f32_e32 v80, 0xbfb8aa3b, v86
	v_mul_f32_e32 v81, 0xbfb8aa3b, v87
	s_nop 1
	v_mov_b32_e32 v86, v172
	v_mov_b32_e32 v87, v173
	v_mov_b32_e32 v88, v174
	v_mov_b32_e32 v89, v175
	v_lshlrev_b32_e32 v78, 16, v74
	v_and_b32_e32 v79, 0xffff0000, v74
	v_mul_f32_e32 v74, 0xbfb8aa3b, v78
	v_mul_f32_e32 v75, 0xbfb8aa3b, v79
	v_exp_f32_e32 v74, v74
	v_exp_f32_e32 v75, v75
	v_exp_f32_e32 v76, v76
	v_exp_f32_e32 v77, v77
	v_mul_f32_e32 v78, 0xbfb8aa3b, v82
	v_mul_f32_e32 v79, 0xbfb8aa3b, v83
	v_exp_f32_e32 v78, v78
	v_exp_f32_e32 v79, v79
	v_exp_f32_e32 v80, v80
	v_exp_f32_e32 v81, v81
	v_add_f32_e32 v74, 1.0, v74
	v_add_f32_e32 v75, 1.0, v75
	v_rcp_f32_e32 v74, v74
	v_rcp_f32_e32 v75, v75
	v_add_f32_e32 v76, 1.0, v76
	v_add_f32_e32 v77, 1.0, v77
	v_rcp_f32_e32 v76, v76
	v_rcp_f32_e32 v77, v77
	v_add_f32_e32 v78, 1.0, v78
	v_add_f32_e32 v79, 1.0, v79
	v_rcp_f32_e32 v78, v78
	v_rcp_f32_e32 v79, v79
	v_add_f32_e32 v80, 1.0, v80
	v_add_f32_e32 v81, 1.0, v81
	v_rcp_f32_e32 v80, v80
	v_rcp_f32_e32 v81, v81
	s_nop 0
	v_lshlrev_b32_e32 v82, 16, v86
	v_and_b32_e32 v83, 0xffff0000, v86
	v_pk_fma_f32 v[70:71], v[70:71], v[74:75], v[82:83]
	v_lshlrev_b32_e32 v74, 16, v87
	v_and_b32_e32 v75, 0xffff0000, v87
	v_pk_fma_f32 v[72:73], v[72:73], v[76:77], v[74:75]
	v_lshlrev_b32_e32 v74, 16, v88
	v_and_b32_e32 v75, 0xffff0000, v88
	v_pk_fma_f32 v[74:75], v[66:67], v[78:79], v[74:75]
	v_lshlrev_b32_e32 v66, 16, v89
	v_and_b32_e32 v67, 0xffff0000, v89
	v_pk_fma_f32 v[76:77], v[68:69], v[80:81], v[66:67]
	v_cvt_pk_bf16_f32 v66, v70, v71
	v_cvt_pk_bf16_f32 v67, v72, v73
	v_cvt_pk_bf16_f32 v68, v74, v75
	v_cvt_pk_bf16_f32 v69, v76, v77
	flat_store_dwordx4 v[84:85], v[66:69] offset:256
	s_nop 1
	v_add_u32_e32 v66, 0x80, v144
	v_ashrrev_i32_e32 v67, 31, v66
	v_mad_i64_i32 v[70:71], s[28:29], v66, s95, v[142:143]
	v_lshlrev_b64 v[66:67], 11, v[66:67]
	v_lshl_add_u64 v[70:71], v[70:71], 0, v[140:141]
	v_lshl_add_u64 v[68:69], s[26:27], 0, v[66:67]
	v_lshl_add_u64 v[66:67], v[70:71], 0, s[46:47]
	v_add_co_u32_e32 v70, vcc, s16, v70
	v_lshl_add_u64 v[68:69], v[68:69], 0, v[140:141]
	s_nop 0
	v_addc_co_u32_e32 v71, vcc, 0, v71, vcc
	s_nop 1
	v_mov_b32_e32 v70, v176
	v_mov_b32_e32 v71, v177
	v_mov_b32_e32 v72, v178
	v_mov_b32_e32 v73, v179
	s_nop 0
	v_lshlrev_b32_e32 v74, 16, v70
	v_and_b32_e32 v70, 0xffff0000, v70
	v_mul_f32_e32 v70, 0xbfb8aa3b, v70
	v_exp_f32_e32 v70, v70
	v_lshlrev_b32_e32 v75, 16, v71
	v_lshlrev_b32_e32 v78, 16, v73
	v_and_b32_e32 v79, 0xffff0000, v73
	v_add_f32_e32 v70, 1.0, v70
	v_rcp_f32_e32 v73, v70
	v_mul_f32_e32 v70, 0xbfb8aa3b, v75
	v_exp_f32_e32 v70, v70
	v_and_b32_e32 v71, 0xffff0000, v71
	v_lshlrev_b32_e32 v76, 16, v72
	v_and_b32_e32 v77, 0xffff0000, v72
	v_add_f32_e32 v70, 1.0, v70
	v_mul_f32_e32 v72, 0xbfb8aa3b, v74
	v_rcp_f32_e32 v74, v70
	v_mul_f32_e32 v70, 0xbfb8aa3b, v71
	v_exp_f32_e32 v70, v70
	v_mul_f32_e32 v71, 0xbfb8aa3b, v79
	v_exp_f32_e32 v72, v72
	v_exp_f32_e32 v71, v71
	v_add_f32_e32 v70, 1.0, v70
	v_rcp_f32_e32 v75, v70
	v_mul_f32_e32 v70, 0xbfb8aa3b, v76
	v_exp_f32_e32 v70, v70
	v_add_f32_e32 v72, 1.0, v72
	v_rcp_f32_e32 v72, v72
	v_add_f32_e32 v71, 1.0, v71
	v_add_f32_e32 v70, 1.0, v70
	v_rcp_f32_e32 v76, v70
	v_mul_f32_e32 v70, 0xbfb8aa3b, v77
	v_exp_f32_e32 v70, v70
	v_rcp_f32_e32 v71, v71
	v_add_f32_e32 v70, 1.0, v70
	v_rcp_f32_e32 v77, v70
	v_mul_f32_e32 v70, 0xbfb8aa3b, v78
	s_nop 1
	v_mov_b32_e32 v78, v182
	v_mov_b32_e32 v79, v183
	v_mov_b32_e32 v80, v184
	v_mov_b32_e32 v81, v185
	v_exp_f32_e32 v70, v70
	s_nop 0
	v_lshlrev_b32_e32 v82, 16, v78
	v_add_f32_e32 v70, 1.0, v70
	v_rcp_f32_e32 v70, v70
	v_and_b32_e32 v83, 0xffff0000, v78
	v_pk_fma_f32 v[62:63], v[62:63], v[72:73], v[82:83]
	v_lshlrev_b32_e32 v72, 16, v79
	v_and_b32_e32 v73, 0xffff0000, v79
	v_pk_fma_f32 v[64:65], v[64:65], v[74:75], v[72:73]
	v_lshlrev_b32_e32 v72, 16, v80
	v_and_b32_e32 v73, 0xffff0000, v80
	v_pk_fma_f32 v[72:73], v[58:59], v[76:77], v[72:73]
	v_lshlrev_b32_e32 v58, 16, v81
	v_and_b32_e32 v59, 0xffff0000, v81
	v_pk_fma_f32 v[70:71], v[60:61], v[70:71], v[58:59]
	v_cvt_pk_bf16_f32 v58, v62, v63
	v_cvt_pk_bf16_f32 v59, v64, v65
	v_cvt_pk_bf16_f32 v60, v72, v73
	v_cvt_pk_bf16_f32 v61, v70, v71
	flat_store_dwordx4 v[68:69], v[58:61]
	s_nop 1
	v_mov_b32_e32 v58, v186
	v_mov_b32_e32 v59, v187
	v_mov_b32_e32 v60, v188
	v_mov_b32_e32 v61, v189
	s_nop 0
	v_lshlrev_b32_e32 v64, 16, v59
	v_and_b32_e32 v65, 0xffff0000, v59
	v_lshlrev_b32_e32 v70, 16, v61
	v_and_b32_e32 v71, 0xffff0000, v61
	v_lshlrev_b32_e32 v66, 16, v60
	v_and_b32_e32 v67, 0xffff0000, v60
	v_mul_f32_e32 v60, 0xbfb8aa3b, v64
	v_mul_f32_e32 v61, 0xbfb8aa3b, v65
	v_mul_f32_e32 v64, 0xbfb8aa3b, v70
	v_mul_f32_e32 v65, 0xbfb8aa3b, v71
	s_nop 1
	v_mov_b32_e32 v70, v190
	v_mov_b32_e32 v71, v191
	v_mov_b32_e32 v72, v192
	v_mov_b32_e32 v73, v193
	v_lshlrev_b32_e32 v62, 16, v58
	v_and_b32_e32 v63, 0xffff0000, v58
	v_mul_f32_e32 v58, 0xbfb8aa3b, v62
	v_mul_f32_e32 v59, 0xbfb8aa3b, v63
	v_exp_f32_e32 v58, v58
	v_exp_f32_e32 v59, v59
	v_exp_f32_e32 v60, v60
	v_exp_f32_e32 v61, v61
	v_mul_f32_e32 v62, 0xbfb8aa3b, v66
	v_mul_f32_e32 v63, 0xbfb8aa3b, v67
	v_exp_f32_e32 v62, v62
	v_exp_f32_e32 v63, v63
	v_exp_f32_e32 v64, v64
	v_exp_f32_e32 v65, v65
	v_add_f32_e32 v58, 1.0, v58
	v_add_f32_e32 v59, 1.0, v59
	v_rcp_f32_e32 v58, v58
	v_rcp_f32_e32 v59, v59
	v_add_f32_e32 v60, 1.0, v60
	v_add_f32_e32 v61, 1.0, v61
	v_rcp_f32_e32 v60, v60
	v_rcp_f32_e32 v61, v61
	v_add_f32_e32 v62, 1.0, v62
	v_add_f32_e32 v63, 1.0, v63
	v_rcp_f32_e32 v62, v62
	v_rcp_f32_e32 v63, v63
	v_add_f32_e32 v64, 1.0, v64
	v_add_f32_e32 v65, 1.0, v65
	v_rcp_f32_e32 v64, v64
	v_rcp_f32_e32 v65, v65
	s_nop 0
	v_lshlrev_b32_e32 v66, 16, v70
	v_and_b32_e32 v67, 0xffff0000, v70
	v_pk_fma_f32 v[54:55], v[54:55], v[58:59], v[66:67]
	v_lshlrev_b32_e32 v58, 16, v71
	v_and_b32_e32 v59, 0xffff0000, v71
	v_pk_fma_f32 v[56:57], v[56:57], v[60:61], v[58:59]
	v_lshlrev_b32_e32 v58, 16, v72
	v_and_b32_e32 v59, 0xffff0000, v72
	v_pk_fma_f32 v[58:59], v[50:51], v[62:63], v[58:59]
	v_lshlrev_b32_e32 v50, 16, v73
	v_and_b32_e32 v51, 0xffff0000, v73
	v_pk_fma_f32 v[60:61], v[52:53], v[64:65], v[50:51]
	v_cvt_pk_bf16_f32 v50, v54, v55
	v_cvt_pk_bf16_f32 v51, v56, v57
	v_cvt_pk_bf16_f32 v52, v58, v59
	v_cvt_pk_bf16_f32 v53, v60, v61
	flat_store_dwordx4 v[68:69], v[50:53] offset:256
	s_nop 1
	v_add_u32_e32 v50, 0x90, v144
	v_ashrrev_i32_e32 v51, 31, v50
	v_mad_i64_i32 v[54:55], s[28:29], v50, s95, v[142:143]
	v_lshlrev_b64 v[50:51], 11, v[50:51]
	v_lshl_add_u64 v[54:55], v[54:55], 0, v[140:141]
	v_lshl_add_u64 v[52:53], s[26:27], 0, v[50:51]
	v_lshl_add_u64 v[50:51], v[54:55], 0, s[46:47]
	v_add_co_u32_e32 v54, vcc, s16, v54
	v_lshl_add_u64 v[52:53], v[52:53], 0, v[140:141]
	s_nop 0
	v_addc_co_u32_e32 v55, vcc, 0, v55, vcc
	s_nop 1
	v_mov_b32_e32 v54, v194
	v_mov_b32_e32 v55, v195
	v_mov_b32_e32 v56, v196
	v_mov_b32_e32 v57, v197
	s_nop 0
	v_lshlrev_b32_e32 v58, 16, v54
	v_and_b32_e32 v54, 0xffff0000, v54
	v_mul_f32_e32 v54, 0xbfb8aa3b, v54
	v_exp_f32_e32 v54, v54
	v_lshlrev_b32_e32 v59, 16, v55
	v_lshlrev_b32_e32 v62, 16, v57
	v_and_b32_e32 v63, 0xffff0000, v57
	v_add_f32_e32 v54, 1.0, v54
	v_rcp_f32_e32 v57, v54
	v_mul_f32_e32 v54, 0xbfb8aa3b, v59
	v_exp_f32_e32 v54, v54
	v_and_b32_e32 v55, 0xffff0000, v55
	v_lshlrev_b32_e32 v60, 16, v56
	v_and_b32_e32 v61, 0xffff0000, v56
	v_add_f32_e32 v54, 1.0, v54
	v_mul_f32_e32 v56, 0xbfb8aa3b, v58
	v_rcp_f32_e32 v58, v54
	v_mul_f32_e32 v54, 0xbfb8aa3b, v55
	v_exp_f32_e32 v54, v54
	v_mul_f32_e32 v55, 0xbfb8aa3b, v63
	v_exp_f32_e32 v56, v56
	v_exp_f32_e32 v55, v55
	v_add_f32_e32 v54, 1.0, v54
	v_rcp_f32_e32 v59, v54
	v_mul_f32_e32 v54, 0xbfb8aa3b, v60
	v_exp_f32_e32 v54, v54
	v_add_f32_e32 v56, 1.0, v56
	v_rcp_f32_e32 v56, v56
	v_add_f32_e32 v55, 1.0, v55
	v_add_f32_e32 v54, 1.0, v54
	v_rcp_f32_e32 v60, v54
	v_mul_f32_e32 v54, 0xbfb8aa3b, v61
	v_exp_f32_e32 v54, v54
	v_rcp_f32_e32 v55, v55
	v_add_f32_e32 v54, 1.0, v54
	v_rcp_f32_e32 v61, v54
	v_mul_f32_e32 v54, 0xbfb8aa3b, v62
	s_nop 1
	v_mov_b32_e32 v62, v218
	v_mov_b32_e32 v63, v219
	v_mov_b32_e32 v64, v220
	v_mov_b32_e32 v65, v221
	v_exp_f32_e32 v54, v54
	s_nop 0
	v_lshlrev_b32_e32 v66, 16, v62
	v_add_f32_e32 v54, 1.0, v54
	v_rcp_f32_e32 v54, v54
	v_and_b32_e32 v67, 0xffff0000, v62
	v_pk_fma_f32 v[46:47], v[46:47], v[56:57], v[66:67]
	v_lshlrev_b32_e32 v56, 16, v63
	v_and_b32_e32 v57, 0xffff0000, v63
	v_pk_fma_f32 v[48:49], v[48:49], v[58:59], v[56:57]
	v_lshlrev_b32_e32 v56, 16, v64
	v_and_b32_e32 v57, 0xffff0000, v64
	v_pk_fma_f32 v[56:57], v[42:43], v[60:61], v[56:57]
	v_lshlrev_b32_e32 v42, 16, v65
	v_and_b32_e32 v43, 0xffff0000, v65
	v_pk_fma_f32 v[54:55], v[44:45], v[54:55], v[42:43]
	v_cvt_pk_bf16_f32 v42, v46, v47
	v_cvt_pk_bf16_f32 v43, v48, v49
	v_cvt_pk_bf16_f32 v44, v56, v57
	v_cvt_pk_bf16_f32 v45, v54, v55
	flat_store_dwordx4 v[52:53], v[42:45]
	s_nop 1
	v_mov_b32_e32 v42, v222
	v_mov_b32_e32 v43, v223
	v_mov_b32_e32 v44, v224
	v_mov_b32_e32 v45, v225
	s_nop 0
	v_lshlrev_b32_e32 v48, 16, v43
	v_and_b32_e32 v49, 0xffff0000, v43
	v_lshlrev_b32_e32 v54, 16, v45
	v_and_b32_e32 v55, 0xffff0000, v45
	v_lshlrev_b32_e32 v50, 16, v44
	v_and_b32_e32 v51, 0xffff0000, v44
	v_mul_f32_e32 v44, 0xbfb8aa3b, v48
	v_mul_f32_e32 v45, 0xbfb8aa3b, v49
	v_mul_f32_e32 v48, 0xbfb8aa3b, v54
	v_mul_f32_e32 v49, 0xbfb8aa3b, v55
	s_nop 1
	v_mov_b32_e32 v54, v230
	v_mov_b32_e32 v55, v231
	v_mov_b32_e32 v56, v232
	v_mov_b32_e32 v57, v233
	v_lshlrev_b32_e32 v46, 16, v42
	v_and_b32_e32 v47, 0xffff0000, v42
	v_mul_f32_e32 v42, 0xbfb8aa3b, v46
	v_mul_f32_e32 v43, 0xbfb8aa3b, v47
	v_exp_f32_e32 v42, v42
	v_exp_f32_e32 v43, v43
	v_exp_f32_e32 v44, v44
	v_exp_f32_e32 v45, v45
	v_mul_f32_e32 v46, 0xbfb8aa3b, v50
	v_mul_f32_e32 v47, 0xbfb8aa3b, v51
	v_exp_f32_e32 v46, v46
	v_exp_f32_e32 v47, v47
	v_exp_f32_e32 v48, v48
	v_exp_f32_e32 v49, v49
	v_add_f32_e32 v42, 1.0, v42
	v_add_f32_e32 v43, 1.0, v43
	v_rcp_f32_e32 v42, v42
	v_rcp_f32_e32 v43, v43
	v_add_f32_e32 v44, 1.0, v44
	v_add_f32_e32 v45, 1.0, v45
	v_rcp_f32_e32 v44, v44
	v_rcp_f32_e32 v45, v45
	v_add_f32_e32 v46, 1.0, v46
	v_add_f32_e32 v47, 1.0, v47
	v_rcp_f32_e32 v46, v46
	v_rcp_f32_e32 v47, v47
	v_add_f32_e32 v48, 1.0, v48
	v_add_f32_e32 v49, 1.0, v49
	v_rcp_f32_e32 v48, v48
	v_rcp_f32_e32 v49, v49
	s_nop 0
	v_lshlrev_b32_e32 v50, 16, v54
	v_and_b32_e32 v51, 0xffff0000, v54
	v_pk_fma_f32 v[38:39], v[38:39], v[42:43], v[50:51]
	v_lshlrev_b32_e32 v42, 16, v55
	v_and_b32_e32 v43, 0xffff0000, v55
	v_pk_fma_f32 v[40:41], v[40:41], v[44:45], v[42:43]
	v_lshlrev_b32_e32 v42, 16, v56
	v_and_b32_e32 v43, 0xffff0000, v56
	v_pk_fma_f32 v[42:43], v[34:35], v[46:47], v[42:43]
	v_lshlrev_b32_e32 v34, 16, v57
	v_and_b32_e32 v35, 0xffff0000, v57
	v_pk_fma_f32 v[44:45], v[36:37], v[48:49], v[34:35]
	v_cvt_pk_bf16_f32 v34, v38, v39
	v_cvt_pk_bf16_f32 v35, v40, v41
	v_cvt_pk_bf16_f32 v36, v42, v43
	v_cvt_pk_bf16_f32 v37, v44, v45
	flat_store_dwordx4 v[52:53], v[34:37] offset:256
	s_nop 1
	v_add_u32_e32 v34, 0xa0, v144
	v_ashrrev_i32_e32 v35, 31, v34
	v_mad_i64_i32 v[38:39], s[28:29], v34, s95, v[142:143]
	v_lshlrev_b64 v[34:35], 11, v[34:35]
	v_lshl_add_u64 v[38:39], v[38:39], 0, v[140:141]
	v_lshl_add_u64 v[36:37], s[26:27], 0, v[34:35]
	v_lshl_add_u64 v[34:35], v[38:39], 0, s[46:47]
	v_add_co_u32_e32 v38, vcc, s16, v38
	v_lshl_add_u64 v[36:37], v[36:37], 0, v[140:141]
	s_nop 0
	v_addc_co_u32_e32 v39, vcc, 0, v39, vcc
	s_nop 1
	v_mov_b32_e32 v38, v234
	v_mov_b32_e32 v39, v235
	v_mov_b32_e32 v40, v236
	v_mov_b32_e32 v41, v237
	s_nop 0
	v_lshlrev_b32_e32 v42, 16, v38
	v_and_b32_e32 v38, 0xffff0000, v38
	v_mul_f32_e32 v38, 0xbfb8aa3b, v38
	v_exp_f32_e32 v38, v38
	v_lshlrev_b32_e32 v43, 16, v39
	v_lshlrev_b32_e32 v46, 16, v41
	v_and_b32_e32 v47, 0xffff0000, v41
	v_add_f32_e32 v38, 1.0, v38
	v_rcp_f32_e32 v41, v38
	v_mul_f32_e32 v38, 0xbfb8aa3b, v43
	v_exp_f32_e32 v38, v38
	v_and_b32_e32 v39, 0xffff0000, v39
	v_lshlrev_b32_e32 v44, 16, v40
	v_and_b32_e32 v45, 0xffff0000, v40
	v_add_f32_e32 v38, 1.0, v38
	v_mul_f32_e32 v40, 0xbfb8aa3b, v42
	v_rcp_f32_e32 v42, v38
	v_mul_f32_e32 v38, 0xbfb8aa3b, v39
	v_exp_f32_e32 v38, v38
	v_mul_f32_e32 v39, 0xbfb8aa3b, v47
	v_exp_f32_e32 v40, v40
	v_exp_f32_e32 v39, v39
	v_add_f32_e32 v38, 1.0, v38
	v_rcp_f32_e32 v43, v38
	v_mul_f32_e32 v38, 0xbfb8aa3b, v44
	v_exp_f32_e32 v38, v38
	v_add_f32_e32 v40, 1.0, v40
	v_rcp_f32_e32 v40, v40
	v_add_f32_e32 v39, 1.0, v39
	v_add_f32_e32 v38, 1.0, v38
	v_rcp_f32_e32 v44, v38
	v_mul_f32_e32 v38, 0xbfb8aa3b, v45
	v_exp_f32_e32 v38, v38
	v_rcp_f32_e32 v39, v39
	v_add_f32_e32 v38, 1.0, v38
	v_rcp_f32_e32 v45, v38
	v_mul_f32_e32 v38, 0xbfb8aa3b, v46
	s_nop 1
	v_mov_b32_e32 v46, v238
	v_mov_b32_e32 v47, v239
	v_mov_b32_e32 v48, v240
	v_mov_b32_e32 v49, v241
	v_exp_f32_e32 v38, v38
	s_nop 0
	v_lshlrev_b32_e32 v50, 16, v46
	v_add_f32_e32 v38, 1.0, v38
	v_rcp_f32_e32 v38, v38
	v_and_b32_e32 v51, 0xffff0000, v46
	v_pk_fma_f32 v[30:31], v[30:31], v[40:41], v[50:51]
	v_lshlrev_b32_e32 v40, 16, v47
	v_and_b32_e32 v41, 0xffff0000, v47
	v_pk_fma_f32 v[32:33], v[32:33], v[42:43], v[40:41]
	v_lshlrev_b32_e32 v40, 16, v48
	v_and_b32_e32 v41, 0xffff0000, v48
	v_pk_fma_f32 v[40:41], v[26:27], v[44:45], v[40:41]
	v_lshlrev_b32_e32 v26, 16, v49
	v_and_b32_e32 v27, 0xffff0000, v49
	v_pk_fma_f32 v[38:39], v[28:29], v[38:39], v[26:27]
	v_cvt_pk_bf16_f32 v26, v30, v31
	v_cvt_pk_bf16_f32 v27, v32, v33
	v_cvt_pk_bf16_f32 v28, v40, v41
	v_cvt_pk_bf16_f32 v29, v38, v39
	flat_store_dwordx4 v[36:37], v[26:29]
	s_nop 1
	v_mov_b32_e32 v26, v242
	v_mov_b32_e32 v27, v243
	v_mov_b32_e32 v28, v244
	v_mov_b32_e32 v29, v245
	s_nop 0
	v_lshlrev_b32_e32 v32, 16, v27
	v_and_b32_e32 v33, 0xffff0000, v27
	v_lshlrev_b32_e32 v38, 16, v29
	v_and_b32_e32 v39, 0xffff0000, v29
	v_lshlrev_b32_e32 v34, 16, v28
	v_and_b32_e32 v35, 0xffff0000, v28
	v_mul_f32_e32 v28, 0xbfb8aa3b, v32
	v_mul_f32_e32 v29, 0xbfb8aa3b, v33
	v_mul_f32_e32 v32, 0xbfb8aa3b, v38
	v_mul_f32_e32 v33, 0xbfb8aa3b, v39
	s_nop 1
	v_mov_b32_e32 v38, v248
	v_mov_b32_e32 v39, v249
	v_mov_b32_e32 v40, v250
	v_mov_b32_e32 v41, v251
	v_add_u32_e32 v170, 176, v144
	v_mad_i64_i32 v[168:169], s[100:101], v170, s95, v[246:247]
	global_load_dwordx4 v[168:171], v[168:169], off
	v_add_u32_e32 v174, 176, v144
	v_lshlrev_b32_e32 v174, 11, v174
	v_mad_u64_u32 v[172:173], s[100:101], v174, 1, v[198:199]
	global_load_dwordx4 v[172:175], v[172:173], off
	v_add_u32_e32 v178, 176, v144
	v_mad_i64_i32 v[176:177], s[100:101], v178, s95, v[246:247]
	global_load_dwordx4 v[176:179], v[176:177], off offset:256
	v_add_u32_e32 v184, 176, v144
	v_lshlrev_b32_e32 v184, 11, v184
	v_mad_u64_u32 v[182:183], s[100:101], v184, 1, v[198:199]
	global_load_dwordx4 v[182:185], v[182:183], off offset:256
	v_lshlrev_b32_e32 v30, 16, v26
	v_and_b32_e32 v31, 0xffff0000, v26
	v_mul_f32_e32 v26, 0xbfb8aa3b, v30
	v_mul_f32_e32 v27, 0xbfb8aa3b, v31
	v_exp_f32_e32 v26, v26
	v_exp_f32_e32 v27, v27
	v_exp_f32_e32 v28, v28
	v_exp_f32_e32 v29, v29
	v_mul_f32_e32 v30, 0xbfb8aa3b, v34
	v_mul_f32_e32 v31, 0xbfb8aa3b, v35
	v_exp_f32_e32 v30, v30
	v_exp_f32_e32 v31, v31
	v_exp_f32_e32 v32, v32
	v_exp_f32_e32 v33, v33
	v_add_f32_e32 v26, 1.0, v26
	v_add_f32_e32 v27, 1.0, v27
	v_rcp_f32_e32 v26, v26
	v_rcp_f32_e32 v27, v27
	v_add_f32_e32 v28, 1.0, v28
	v_add_f32_e32 v29, 1.0, v29
	v_rcp_f32_e32 v28, v28
	v_rcp_f32_e32 v29, v29
	v_add_f32_e32 v30, 1.0, v30
	v_add_f32_e32 v31, 1.0, v31
	v_rcp_f32_e32 v30, v30
	v_rcp_f32_e32 v31, v31
	v_add_f32_e32 v32, 1.0, v32
	v_add_f32_e32 v33, 1.0, v33
	v_rcp_f32_e32 v32, v32
	v_rcp_f32_e32 v33, v33
	s_nop 0
	v_lshlrev_b32_e32 v34, 16, v38
	v_and_b32_e32 v35, 0xffff0000, v38
	v_pk_fma_f32 v[22:23], v[22:23], v[26:27], v[34:35]
	v_lshlrev_b32_e32 v26, 16, v39
	v_and_b32_e32 v27, 0xffff0000, v39
	v_pk_fma_f32 v[24:25], v[24:25], v[28:29], v[26:27]
	v_lshlrev_b32_e32 v26, 16, v40
	v_and_b32_e32 v27, 0xffff0000, v40
	v_pk_fma_f32 v[26:27], v[18:19], v[30:31], v[26:27]
	v_lshlrev_b32_e32 v18, 16, v41
	v_and_b32_e32 v19, 0xffff0000, v41
	v_pk_fma_f32 v[28:29], v[20:21], v[32:33], v[18:19]
	v_cvt_pk_bf16_f32 v18, v22, v23
	v_cvt_pk_bf16_f32 v19, v24, v25
	v_cvt_pk_bf16_f32 v20, v26, v27
	v_cvt_pk_bf16_f32 v21, v28, v29
	flat_store_dwordx4 v[36:37], v[18:21] offset:256
	s_nop 1
	v_add_u32_e32 v18, 0xb0, v144
	v_ashrrev_i32_e32 v19, 31, v18
	v_mad_i64_i32 v[22:23], s[28:29], v18, s95, v[142:143]
	v_lshlrev_b64 v[18:19], 11, v[18:19]
	v_lshl_add_u64 v[22:23], v[22:23], 0, v[140:141]
	v_lshl_add_u64 v[20:21], s[26:27], 0, v[18:19]
	v_lshl_add_u64 v[18:19], v[22:23], 0, s[46:47]
	v_add_co_u32_e32 v22, vcc, s16, v22
	v_lshl_add_u64 v[20:21], v[20:21], 0, v[140:141]
	s_nop 0
	v_addc_co_u32_e32 v23, vcc, 0, v23, vcc
	s_waitcnt vmcnt(0)
	s_nop 1
	v_mov_b32_e32 v22, v168
	v_mov_b32_e32 v23, v169
	v_mov_b32_e32 v24, v170
	v_mov_b32_e32 v25, v171
	s_mov_b64 s[26:27], -1
	s_and_b64 vcc, exec, s[2:3]
	s_nop 0
	v_lshlrev_b32_e32 v26, 16, v22
	v_lshlrev_b32_e32 v30, 16, v24
	v_and_b32_e32 v27, 0xffff0000, v22
	v_mul_f32_e32 v22, 0xbfb8aa3b, v26
	v_mul_f32_e32 v26, 0xbfb8aa3b, v30
	v_exp_f32_e32 v26, v26
	v_and_b32_e32 v31, 0xffff0000, v24
	v_lshlrev_b32_e32 v32, 16, v25
	v_and_b32_e32 v33, 0xffff0000, v25
	v_add_f32_e32 v26, 1.0, v26
	v_rcp_f32_e32 v30, v26
	v_mul_f32_e32 v26, 0xbfb8aa3b, v31
	v_exp_f32_e32 v26, v26
	v_lshlrev_b32_e32 v28, 16, v23
	v_and_b32_e32 v29, 0xffff0000, v23
	v_mul_f32_e32 v23, 0xbfb8aa3b, v27
	v_add_f32_e32 v26, 1.0, v26
	v_rcp_f32_e32 v31, v26
	v_mul_f32_e32 v26, 0xbfb8aa3b, v32
	v_exp_f32_e32 v26, v26
	v_mul_f32_e32 v24, 0xbfb8aa3b, v28
	v_mul_f32_e32 v25, 0xbfb8aa3b, v29
	v_exp_f32_e32 v22, v22
	v_add_f32_e32 v26, 1.0, v26
	v_rcp_f32_e32 v32, v26
	v_mul_f32_e32 v26, 0xbfb8aa3b, v33
	v_exp_f32_e32 v26, v26
	v_exp_f32_e32 v23, v23
	v_exp_f32_e32 v24, v24
	v_exp_f32_e32 v25, v25
	v_add_f32_e32 v26, 1.0, v26
	v_rcp_f32_e32 v33, v26
	s_nop 1
	v_mov_b32_e32 v26, v172
	v_mov_b32_e32 v27, v173
	v_mov_b32_e32 v28, v174
	v_mov_b32_e32 v29, v175
	v_add_f32_e32 v22, 1.0, v22
	v_add_f32_e32 v23, 1.0, v23
	v_rcp_f32_e32 v22, v22
	v_rcp_f32_e32 v23, v23
	v_add_f32_e32 v24, 1.0, v24
	v_add_f32_e32 v25, 1.0, v25
	v_rcp_f32_e32 v24, v24
	v_rcp_f32_e32 v25, v25
	s_nop 0
	v_lshlrev_b32_e32 v34, 16, v26
	v_and_b32_e32 v35, 0xffff0000, v26
	v_pk_fma_f32 v[14:15], v[14:15], v[22:23], v[34:35]
	v_lshlrev_b32_e32 v22, 16, v27
	v_and_b32_e32 v23, 0xffff0000, v27
	v_pk_fma_f32 v[16:17], v[16:17], v[24:25], v[22:23]
	v_lshlrev_b32_e32 v22, 16, v28
	v_and_b32_e32 v23, 0xffff0000, v28
	v_pk_fma_f32 v[22:23], v[10:11], v[30:31], v[22:23]
	v_lshlrev_b32_e32 v10, 16, v29
	v_and_b32_e32 v11, 0xffff0000, v29
	v_pk_fma_f32 v[24:25], v[12:13], v[32:33], v[10:11]
	v_cvt_pk_bf16_f32 v10, v14, v15
	v_cvt_pk_bf16_f32 v11, v16, v17
	v_cvt_pk_bf16_f32 v12, v22, v23
	v_cvt_pk_bf16_f32 v13, v24, v25
	flat_store_dwordx4 v[20:21], v[10:13]
	s_nop 1
	v_mov_b32_e32 v10, v176
	v_mov_b32_e32 v11, v177
	v_mov_b32_e32 v12, v178
	v_mov_b32_e32 v13, v179
	s_nop 0
	v_lshlrev_b32_e32 v14, 16, v10
	v_and_b32_e32 v10, 0xffff0000, v10
	v_mul_f32_e32 v10, 0xbfb8aa3b, v10
	v_exp_f32_e32 v10, v10
	v_lshlrev_b32_e32 v16, 16, v11
	v_and_b32_e32 v11, 0xffff0000, v11
	v_lshlrev_b32_e32 v18, 16, v12
	v_add_f32_e32 v10, 1.0, v10
	v_rcp_f32_e32 v15, v10
	v_mul_f32_e32 v10, 0xbfb8aa3b, v16
	v_exp_f32_e32 v10, v10
	v_and_b32_e32 v12, 0xffff0000, v12
	v_lshlrev_b32_e32 v22, 16, v13
	v_and_b32_e32 v13, 0xffff0000, v13
	v_add_f32_e32 v10, 1.0, v10
	v_rcp_f32_e32 v16, v10
	v_mul_f32_e32 v10, 0xbfb8aa3b, v11
	v_exp_f32_e32 v10, v10
	v_mul_f32_e32 v14, 0xbfb8aa3b, v14
	v_exp_f32_e32 v14, v14
	v_add_f32_e32 v10, 1.0, v10
	v_rcp_f32_e32 v17, v10
	v_mul_f32_e32 v10, 0xbfb8aa3b, v18
	v_exp_f32_e32 v10, v10
	v_add_f32_e32 v14, 1.0, v14
	v_rcp_f32_e32 v14, v14
	v_add_f32_e32 v10, 1.0, v10
	v_rcp_f32_e32 v18, v10
	v_mul_f32_e32 v10, 0xbfb8aa3b, v12
	v_exp_f32_e32 v10, v10
	s_nop 0
	v_add_f32_e32 v10, 1.0, v10
	v_rcp_f32_e32 v19, v10
	v_mul_f32_e32 v10, 0xbfb8aa3b, v22
	v_exp_f32_e32 v10, v10
	s_nop 0
	v_add_f32_e32 v10, 1.0, v10
	v_rcp_f32_e32 v22, v10
	v_mul_f32_e32 v10, 0xbfb8aa3b, v13
	v_exp_f32_e32 v10, v10
	s_nop 0
	v_add_f32_e32 v10, 1.0, v10
	v_rcp_f32_e32 v23, v10
	s_nop 1
	v_mov_b32_e32 v10, v182
	v_mov_b32_e32 v11, v183
	v_mov_b32_e32 v12, v184
	v_mov_b32_e32 v13, v185
	s_nop 0
	v_lshlrev_b32_e32 v24, 16, v10
	v_and_b32_e32 v25, 0xffff0000, v10
	v_lshlrev_b32_e32 v10, 16, v11
	v_and_b32_e32 v11, 0xffff0000, v11
	v_pk_fma_f32 v[8:9], v[8:9], v[16:17], v[10:11]
	v_lshlrev_b32_e32 v10, 16, v12
	v_and_b32_e32 v11, 0xffff0000, v12
	v_pk_fma_f32 v[10:11], v[2:3], v[18:19], v[10:11]
	v_lshlrev_b32_e32 v2, 16, v13
	v_and_b32_e32 v3, 0xffff0000, v13
	v_pk_fma_f32 v[6:7], v[6:7], v[14:15], v[24:25]
	v_pk_fma_f32 v[12:13], v[4:5], v[22:23], v[2:3]
	v_cvt_pk_bf16_f32 v2, v6, v7
	v_cvt_pk_bf16_f32 v3, v8, v9
	v_cvt_pk_bf16_f32 v4, v10, v11
	v_cvt_pk_bf16_f32 v5, v12, v13
	flat_store_dwordx4 v[20:21], v[2:5] offset:256
	s_cbranch_vccnz .LBB0_1036
	s_andn2_b64 vcc, exec, s[18:19]
	s_cbranch_vccnz .LBB0_1035
	s_barrier
	s_branch .LBB0_1035
